# hand-scheduled RWKV scan loop (LDS prefetch 2 steps ahead, deferred y-reduction), MLA attention LDS pipelining, prep LoRA-up loop double-buffered weights, CU-mates of scan workgroups skip attention qu
# speedup vs baseline: 1.0337x; 1.0331x over previous
; #define LBAR() asm volatile("s_waitcnt lgkmcnt(0)\n\ts_barrier" ::: "memory")
; #define SC_STORE(R, B)                                                \
;   _Pragma("unroll") for (int i = 0; i < 6; ++i) *(f32x4*)(buf + (B) * SC_CH * SC_STEPF + pf[i]) = R[i];
; __device__ __forceinline__ void scan_unit(const Params p, int u, char* smem) {
;     ...
;   __syncthreads();
;   __builtin_amdgcn_s_setprio(3);
;   SC_LOAD(lregA, 0);
;   SC_STORE(lregA, 0);
;   SC_LOAD(lregB, 1);
;   __syncthreads();
;   for (int c = 0; c < nch; c += 2) {
;     SC_LOAD(lregA, c + 2);
;     SC_COMPUTE(c, 0);
;     SC_STORE(lregB, 1);
;     LBAR();
;     SC_LOAD(lregB, c + 3);
.LBB0_99:
	ds_read_b128 v[56:59], v129
	ds_read_b128 v[60:63], v129 offset:256
	ds_read_b128 v[64:67], v129 offset:512
	ds_read_b128 v[68:71], v129 offset:768
	ds_read_b128 v[72:75], v129 offset:1024
	ds_read_b32 v76, v131 offset:1280
	ds_read_b128 v[80:83], v129 offset:1344
	ds_read_b128 v[84:87], v129 offset:1600
	ds_read_b128 v[88:91], v129 offset:1856
	ds_read_b128 v[92:95], v129 offset:2112
	ds_read_b128 v[96:99], v129 offset:2368
	ds_read_b32 v100, v131 offset:2624
	s_add_i32 s2, s3, 2
	s_add_i32 s3, s3, 4
	s_min_u32 s3, s3, 0x1ff
	s_mul_i32 s3, s3, s0
	v_add_u32_e32 v112, s3, v168
	v_add_u32_e32 v113, s3, v116
	v_add_u32_e32 v114, s3, v118
	v_add_u32_e32 v115, s3, v120
	v_add_u32_e32 v128, s3, v122
	v_add_u32_e32 v130, s3, v124
	v_pk_mul_f32 v[108:109], v[162:163], v[54:55]
	v_pk_fma_f32 v[108:109], v[160:161], v[52:53], v[108:109]
	v_add_f32_e32 v108, v108, v109
	global_load_dwordx4 v[28:31], v112, s[96:97]
	global_load_dwordx4 v[32:35], v113, s[96:97]
	v_add_f32_dpp v108, v108, v108 quad_perm:[1,0,3,2] row_mask:0xf bank_mask:0xf bound_ctrl:1
	global_load_dwordx4 v[36:39], v114, s[96:97]
	global_load_dwordx4 v[40:43], v115, s[96:97]
	v_add_f32_dpp v108, v108, v108 quad_perm:[2,3,0,1] row_mask:0xf bank_mask:0xf bound_ctrl:1
	global_load_dwordx4 v[44:47], v128, s[96:97]
	global_load_dwordx4 v[24:27], v130, s[96:97]
	v_add_f32_dpp v108, v108, v108 row_half_mirror row_mask:0xf bank_mask:0xf bound_ctrl:1
	s_nop 0
	s_nop 0
	v_add_f32_dpp v108, v108, v108 row_mirror row_mask:0xf bank_mask:0xf bound_ctrl:1
	v_cndmask_b32_e64 v110, v110, v108, s[66:67]
	s_cmp_eq_u32 s2, 0
	s_cbranch_scc1 .Lscan_skip_first
	global_store_dword v111, v110, s[96:97]
.Lscan_skip_first:
	s_waitcnt lgkmcnt(6)
	v_pk_mul_f32 v[102:103], v[52:53], v[56:57]
	v_pk_fma_f32 v[102:103], v[54:55], v[58:59], v[102:103]
	v_pk_mul_f32 v[104:105], v[68:69], v[76:77] op_sel_hi:[1,0]
	v_add_f32_e32 v102, v102, v103
	v_pk_mul_f32 v[106:107], v[70:71], v[76:77] op_sel_hi:[1,0]
	ds_read_b128 v[136:139], v129 offset:2688
	v_add_f32_dpp v102, v102, v102 quad_perm:[1,0,3,2] row_mask:0xf bank_mask:0xf bound_ctrl:1
	v_pk_fma_f32 v[104:105], v[52:53], v[60:61], v[104:105]
	ds_read_b128 v[140:143], v129 offset:2944
	v_add_f32_dpp v102, v102, v102 quad_perm:[2,3,0,1] row_mask:0xf bank_mask:0xf bound_ctrl:1
	v_pk_fma_f32 v[106:107], v[54:55], v[62:63], v[106:107]
	ds_read_b128 v[144:147], v129 offset:3200
	v_add_f32_dpp v102, v102, v102 row_half_mirror row_mask:0xf bank_mask:0xf bound_ctrl:1
	ds_read_b128 v[148:151], v129 offset:3456
	ds_read_b128 v[152:155], v129 offset:3712
	v_add_f32_dpp v102, v102, v102 row_mirror row_mask:0xf bank_mask:0xf bound_ctrl:1
	v_pk_fma_f32 v[52:53], v[64:65], v[102:103], v[104:105] op_sel_hi:[1,0,1] neg_lo:[0,1,0] neg_hi:[0,1,0]
	v_pk_fma_f32 v[54:55], v[66:67], v[102:103], v[106:107] op_sel_hi:[1,0,1] neg_lo:[0,1,0] neg_hi:[0,1,0]
	ds_read_b32 v156, v131 offset:3968
	s_waitcnt lgkmcnt(6)
	v_pk_mul_f32 v[102:103], v[52:53], v[80:81]
	v_pk_mul_f32 v[108:109], v[74:75], v[54:55]
	v_pk_fma_f32 v[102:103], v[54:55], v[82:83], v[102:103]
	v_pk_fma_f32 v[108:109], v[72:73], v[52:53], v[108:109]
	v_pk_mul_f32 v[104:105], v[92:93], v[100:101] op_sel_hi:[1,0]
	v_add_f32_e32 v102, v102, v103
	v_add_f32_e32 v108, v108, v109
	v_pk_mul_f32 v[106:107], v[94:95], v[100:101] op_sel_hi:[1,0]
	v_add_f32_dpp v102, v102, v102 quad_perm:[1,0,3,2] row_mask:0xf bank_mask:0xf bound_ctrl:1
	v_pk_fma_f32 v[104:105], v[52:53], v[84:85], v[104:105]
	v_add_f32_dpp v108, v108, v108 quad_perm:[1,0,3,2] row_mask:0xf bank_mask:0xf bound_ctrl:1
	v_add_f32_dpp v102, v102, v102 quad_perm:[2,3,0,1] row_mask:0xf bank_mask:0xf bound_ctrl:1
	v_pk_fma_f32 v[106:107], v[54:55], v[86:87], v[106:107]
	v_add_f32_dpp v108, v108, v108 quad_perm:[2,3,0,1] row_mask:0xf bank_mask:0xf bound_ctrl:1
	v_add_f32_dpp v102, v102, v102 row_half_mirror row_mask:0xf bank_mask:0xf bound_ctrl:1
	ds_read_b128 v[56:59], v129 offset:4032
	v_add_f32_dpp v108, v108, v108 row_half_mirror row_mask:0xf bank_mask:0xf bound_ctrl:1
	v_add_f32_dpp v102, v102, v102 row_mirror row_mask:0xf bank_mask:0xf bound_ctrl:1
	ds_read_b128 v[60:63], v129 offset:4288
	v_add_f32_dpp v108, v108, v108 row_mirror row_mask:0xf bank_mask:0xf bound_ctrl:1
	v_pk_fma_f32 v[52:53], v[88:89], v[102:103], v[104:105] op_sel_hi:[1,0,1] neg_lo:[0,1,0] neg_hi:[0,1,0]
	v_pk_fma_f32 v[54:55], v[90:91], v[102:103], v[106:107] op_sel_hi:[1,0,1] neg_lo:[0,1,0] neg_hi:[0,1,0]
	v_cndmask_b32_e32 v110, 0, v108, vcc
	ds_read_b128 v[64:67], v129 offset:4544
	ds_read_b128 v[68:71], v129 offset:4800
	ds_read_b128 v[72:75], v129 offset:5056
	ds_read_b32 v76, v131 offset:5312
	s_waitcnt lgkmcnt(6)
	v_pk_mul_f32 v[102:103], v[52:53], v[136:137]
	v_pk_mul_f32 v[108:109], v[98:99], v[54:55]
	v_pk_fma_f32 v[102:103], v[54:55], v[138:139], v[102:103]
	v_pk_fma_f32 v[108:109], v[96:97], v[52:53], v[108:109]
	v_pk_mul_f32 v[104:105], v[148:149], v[156:157] op_sel_hi:[1,0]
	v_add_f32_e32 v102, v102, v103
	v_add_f32_e32 v108, v108, v109
	v_pk_mul_f32 v[106:107], v[150:151], v[156:157] op_sel_hi:[1,0]
	v_add_f32_dpp v102, v102, v102 quad_perm:[1,0,3,2] row_mask:0xf bank_mask:0xf bound_ctrl:1
	v_pk_fma_f32 v[104:105], v[52:53], v[140:141], v[104:105]
	v_add_f32_dpp v108, v108, v108 quad_perm:[1,0,3,2] row_mask:0xf bank_mask:0xf bound_ctrl:1
	v_add_f32_dpp v102, v102, v102 quad_perm:[2,3,0,1] row_mask:0xf bank_mask:0xf bound_ctrl:1
	v_pk_fma_f32 v[106:107], v[54:55], v[142:143], v[106:107]
	v_add_f32_dpp v108, v108, v108 quad_perm:[2,3,0,1] row_mask:0xf bank_mask:0xf bound_ctrl:1
	v_add_f32_dpp v102, v102, v102 row_half_mirror row_mask:0xf bank_mask:0xf bound_ctrl:1
	ds_read_b128 v[80:83], v129 offset:5376
	v_add_f32_dpp v108, v108, v108 row_half_mirror row_mask:0xf bank_mask:0xf bound_ctrl:1
	v_add_f32_dpp v102, v102, v102 row_mirror row_mask:0xf bank_mask:0xf bound_ctrl:1
	ds_read_b128 v[84:87], v129 offset:5632
	v_add_f32_dpp v108, v108, v108 row_mirror row_mask:0xf bank_mask:0xf bound_ctrl:1
	v_pk_fma_f32 v[52:53], v[144:145], v[102:103], v[104:105] op_sel_hi:[1,0,1] neg_lo:[0,1,0] neg_hi:[0,1,0]
	v_pk_fma_f32 v[54:55], v[146:147], v[102:103], v[106:107] op_sel_hi:[1,0,1] neg_lo:[0,1,0] neg_hi:[0,1,0]
	v_cndmask_b32_e64 v110, v110, v108, s[38:39]
	ds_read_b128 v[88:91], v129 offset:5888
	ds_read_b128 v[92:95], v129 offset:6144
	ds_read_b128 v[96:99], v129 offset:6400
	ds_read_b32 v100, v131 offset:6656
	s_waitcnt lgkmcnt(6)
	v_pk_mul_f32 v[102:103], v[52:53], v[56:57]
	v_pk_mul_f32 v[108:109], v[154:155], v[54:55]
	v_pk_fma_f32 v[102:103], v[54:55], v[58:59], v[102:103]
	v_pk_fma_f32 v[108:109], v[152:153], v[52:53], v[108:109]
	v_pk_mul_f32 v[104:105], v[68:69], v[76:77] op_sel_hi:[1,0]
	v_add_f32_e32 v102, v102, v103
	v_add_f32_e32 v108, v108, v109
	v_pk_mul_f32 v[106:107], v[70:71], v[76:77] op_sel_hi:[1,0]
	v_add_f32_dpp v102, v102, v102 quad_perm:[1,0,3,2] row_mask:0xf bank_mask:0xf bound_ctrl:1
	v_pk_fma_f32 v[104:105], v[52:53], v[60:61], v[104:105]
	v_add_f32_dpp v108, v108, v108 quad_perm:[1,0,3,2] row_mask:0xf bank_mask:0xf bound_ctrl:1
	v_add_f32_dpp v102, v102, v102 quad_perm:[2,3,0,1] row_mask:0xf bank_mask:0xf bound_ctrl:1
	v_pk_fma_f32 v[106:107], v[54:55], v[62:63], v[106:107]
	v_add_f32_dpp v108, v108, v108 quad_perm:[2,3,0,1] row_mask:0xf bank_mask:0xf bound_ctrl:1
	v_add_f32_dpp v102, v102, v102 row_half_mirror row_mask:0xf bank_mask:0xf bound_ctrl:1
	ds_read_b128 v[136:139], v129 offset:6720
	v_add_f32_dpp v108, v108, v108 row_half_mirror row_mask:0xf bank_mask:0xf bound_ctrl:1
	v_add_f32_dpp v102, v102, v102 row_mirror row_mask:0xf bank_mask:0xf bound_ctrl:1
	ds_read_b128 v[140:143], v129 offset:6976
	v_add_f32_dpp v108, v108, v108 row_mirror row_mask:0xf bank_mask:0xf bound_ctrl:1
	v_pk_fma_f32 v[52:53], v[64:65], v[102:103], v[104:105] op_sel_hi:[1,0,1] neg_lo:[0,1,0] neg_hi:[0,1,0]
	v_pk_fma_f32 v[54:55], v[66:67], v[102:103], v[106:107] op_sel_hi:[1,0,1] neg_lo:[0,1,0] neg_hi:[0,1,0]
	v_cndmask_b32_e64 v110, v110, v108, s[40:41]
	ds_read_b128 v[144:147], v129 offset:7232
	ds_read_b128 v[148:151], v129 offset:7488
	ds_read_b128 v[152:155], v129 offset:7744
	ds_read_b32 v156, v131 offset:8000
	s_waitcnt lgkmcnt(6)
	v_pk_mul_f32 v[102:103], v[52:53], v[80:81]
	v_pk_mul_f32 v[108:109], v[74:75], v[54:55]
	v_pk_fma_f32 v[102:103], v[54:55], v[82:83], v[102:103]
	v_pk_fma_f32 v[108:109], v[72:73], v[52:53], v[108:109]
	v_pk_mul_f32 v[104:105], v[92:93], v[100:101] op_sel_hi:[1,0]
	v_add_f32_e32 v102, v102, v103
	v_add_f32_e32 v108, v108, v109
	v_pk_mul_f32 v[106:107], v[94:95], v[100:101] op_sel_hi:[1,0]
	v_add_f32_dpp v102, v102, v102 quad_perm:[1,0,3,2] row_mask:0xf bank_mask:0xf bound_ctrl:1
	v_pk_fma_f32 v[104:105], v[52:53], v[84:85], v[104:105]
	v_add_f32_dpp v108, v108, v108 quad_perm:[1,0,3,2] row_mask:0xf bank_mask:0xf bound_ctrl:1
	v_add_f32_dpp v102, v102, v102 quad_perm:[2,3,0,1] row_mask:0xf bank_mask:0xf bound_ctrl:1
	v_pk_fma_f32 v[106:107], v[54:55], v[86:87], v[106:107]
	v_add_f32_dpp v108, v108, v108 quad_perm:[2,3,0,1] row_mask:0xf bank_mask:0xf bound_ctrl:1
	v_add_f32_dpp v102, v102, v102 row_half_mirror row_mask:0xf bank_mask:0xf bound_ctrl:1
	ds_read_b128 v[56:59], v129 offset:8064
	v_add_f32_dpp v108, v108, v108 row_half_mirror row_mask:0xf bank_mask:0xf bound_ctrl:1
	v_add_f32_dpp v102, v102, v102 row_mirror row_mask:0xf bank_mask:0xf bound_ctrl:1
	ds_read_b128 v[60:63], v129 offset:8320
	v_add_f32_dpp v108, v108, v108 row_mirror row_mask:0xf bank_mask:0xf bound_ctrl:1
	v_pk_fma_f32 v[52:53], v[88:89], v[102:103], v[104:105] op_sel_hi:[1,0,1] neg_lo:[0,1,0] neg_hi:[0,1,0]
	v_pk_fma_f32 v[54:55], v[90:91], v[102:103], v[106:107] op_sel_hi:[1,0,1] neg_lo:[0,1,0] neg_hi:[0,1,0]
	v_cndmask_b32_e64 v110, v110, v108, s[42:43]
	ds_read_b128 v[64:67], v129 offset:8576
	ds_read_b128 v[68:71], v129 offset:8832
	ds_read_b128 v[72:75], v129 offset:9088
	ds_read_b32 v76, v131 offset:9344
	s_waitcnt lgkmcnt(6)
	v_pk_mul_f32 v[102:103], v[52:53], v[136:137]
	v_pk_mul_f32 v[108:109], v[98:99], v[54:55]
	v_pk_fma_f32 v[102:103], v[54:55], v[138:139], v[102:103]
	v_pk_fma_f32 v[108:109], v[96:97], v[52:53], v[108:109]
	v_pk_mul_f32 v[104:105], v[148:149], v[156:157] op_sel_hi:[1,0]
	v_add_f32_e32 v102, v102, v103
	v_add_f32_e32 v108, v108, v109
	v_pk_mul_f32 v[106:107], v[150:151], v[156:157] op_sel_hi:[1,0]
	v_add_f32_dpp v102, v102, v102 quad_perm:[1,0,3,2] row_mask:0xf bank_mask:0xf bound_ctrl:1
	v_pk_fma_f32 v[104:105], v[52:53], v[140:141], v[104:105]
	v_add_f32_dpp v108, v108, v108 quad_perm:[1,0,3,2] row_mask:0xf bank_mask:0xf bound_ctrl:1
	v_add_f32_dpp v102, v102, v102 quad_perm:[2,3,0,1] row_mask:0xf bank_mask:0xf bound_ctrl:1
	v_pk_fma_f32 v[106:107], v[54:55], v[142:143], v[106:107]
	v_add_f32_dpp v108, v108, v108 quad_perm:[2,3,0,1] row_mask:0xf bank_mask:0xf bound_ctrl:1
	v_add_f32_dpp v102, v102, v102 row_half_mirror row_mask:0xf bank_mask:0xf bound_ctrl:1
	ds_read_b128 v[80:83], v129 offset:9408
	v_add_f32_dpp v108, v108, v108 row_half_mirror row_mask:0xf bank_mask:0xf bound_ctrl:1
	v_add_f32_dpp v102, v102, v102 row_mirror row_mask:0xf bank_mask:0xf bound_ctrl:1
	ds_read_b128 v[84:87], v129 offset:9664
	v_add_f32_dpp v108, v108, v108 row_mirror row_mask:0xf bank_mask:0xf bound_ctrl:1
	v_pk_fma_f32 v[52:53], v[144:145], v[102:103], v[104:105] op_sel_hi:[1,0,1] neg_lo:[0,1,0] neg_hi:[0,1,0]
	v_pk_fma_f32 v[54:55], v[146:147], v[102:103], v[106:107] op_sel_hi:[1,0,1] neg_lo:[0,1,0] neg_hi:[0,1,0]
	v_cndmask_b32_e64 v110, v110, v108, s[44:45]
	ds_read_b128 v[88:91], v129 offset:9920
	ds_read_b128 v[92:95], v129 offset:10176
	ds_read_b128 v[96:99], v129 offset:10432
	ds_read_b32 v100, v131 offset:10688
	s_waitcnt lgkmcnt(6)
	v_pk_mul_f32 v[102:103], v[52:53], v[56:57]
	v_pk_mul_f32 v[108:109], v[154:155], v[54:55]
	v_pk_fma_f32 v[102:103], v[54:55], v[58:59], v[102:103]
	v_pk_fma_f32 v[108:109], v[152:153], v[52:53], v[108:109]
	v_pk_mul_f32 v[104:105], v[68:69], v[76:77] op_sel_hi:[1,0]
	v_add_f32_e32 v102, v102, v103
	v_add_f32_e32 v108, v108, v109
	v_pk_mul_f32 v[106:107], v[70:71], v[76:77] op_sel_hi:[1,0]
	v_add_f32_dpp v102, v102, v102 quad_perm:[1,0,3,2] row_mask:0xf bank_mask:0xf bound_ctrl:1
	v_pk_fma_f32 v[104:105], v[52:53], v[60:61], v[104:105]
	v_add_f32_dpp v108, v108, v108 quad_perm:[1,0,3,2] row_mask:0xf bank_mask:0xf bound_ctrl:1
	v_add_f32_dpp v102, v102, v102 quad_perm:[2,3,0,1] row_mask:0xf bank_mask:0xf bound_ctrl:1
	v_pk_fma_f32 v[106:107], v[54:55], v[62:63], v[106:107]
	v_add_f32_dpp v108, v108, v108 quad_perm:[2,3,0,1] row_mask:0xf bank_mask:0xf bound_ctrl:1
	v_add_f32_dpp v102, v102, v102 row_half_mirror row_mask:0xf bank_mask:0xf bound_ctrl:1
	ds_read_b128 v[136:139], v129 offset:10752
	v_add_f32_dpp v108, v108, v108 row_half_mirror row_mask:0xf bank_mask:0xf bound_ctrl:1
	v_add_f32_dpp v102, v102, v102 row_mirror row_mask:0xf bank_mask:0xf bound_ctrl:1
	ds_read_b128 v[140:143], v129 offset:11008
	v_add_f32_dpp v108, v108, v108 row_mirror row_mask:0xf bank_mask:0xf bound_ctrl:1
	v_pk_fma_f32 v[52:53], v[64:65], v[102:103], v[104:105] op_sel_hi:[1,0,1] neg_lo:[0,1,0] neg_hi:[0,1,0]
	v_pk_fma_f32 v[54:55], v[66:67], v[102:103], v[106:107] op_sel_hi:[1,0,1] neg_lo:[0,1,0] neg_hi:[0,1,0]
	v_cndmask_b32_e64 v110, v110, v108, s[46:47]
	ds_read_b128 v[144:147], v129 offset:11264
	ds_read_b128 v[148:151], v129 offset:11520
	ds_read_b128 v[152:155], v129 offset:11776
	ds_read_b32 v156, v131 offset:12032
	s_waitcnt lgkmcnt(6)
	v_pk_mul_f32 v[102:103], v[52:53], v[80:81]
	v_pk_mul_f32 v[108:109], v[74:75], v[54:55]
	v_pk_fma_f32 v[102:103], v[54:55], v[82:83], v[102:103]
	v_pk_fma_f32 v[108:109], v[72:73], v[52:53], v[108:109]
	v_pk_mul_f32 v[104:105], v[92:93], v[100:101] op_sel_hi:[1,0]
	v_add_f32_e32 v102, v102, v103
	v_add_f32_e32 v108, v108, v109
	v_pk_mul_f32 v[106:107], v[94:95], v[100:101] op_sel_hi:[1,0]
	v_add_f32_dpp v102, v102, v102 quad_perm:[1,0,3,2] row_mask:0xf bank_mask:0xf bound_ctrl:1
	v_pk_fma_f32 v[104:105], v[52:53], v[84:85], v[104:105]
	v_add_f32_dpp v108, v108, v108 quad_perm:[1,0,3,2] row_mask:0xf bank_mask:0xf bound_ctrl:1
	v_add_f32_dpp v102, v102, v102 quad_perm:[2,3,0,1] row_mask:0xf bank_mask:0xf bound_ctrl:1
	v_pk_fma_f32 v[106:107], v[54:55], v[86:87], v[106:107]
	v_add_f32_dpp v108, v108, v108 quad_perm:[2,3,0,1] row_mask:0xf bank_mask:0xf bound_ctrl:1
	v_add_f32_dpp v102, v102, v102 row_half_mirror row_mask:0xf bank_mask:0xf bound_ctrl:1
	ds_read_b128 v[56:59], v129 offset:12096
	v_add_f32_dpp v108, v108, v108 row_half_mirror row_mask:0xf bank_mask:0xf bound_ctrl:1
	v_add_f32_dpp v102, v102, v102 row_mirror row_mask:0xf bank_mask:0xf bound_ctrl:1
	ds_read_b128 v[60:63], v129 offset:12352
	v_add_f32_dpp v108, v108, v108 row_mirror row_mask:0xf bank_mask:0xf bound_ctrl:1
	v_pk_fma_f32 v[52:53], v[88:89], v[102:103], v[104:105] op_sel_hi:[1,0,1] neg_lo:[0,1,0] neg_hi:[0,1,0]
	v_pk_fma_f32 v[54:55], v[90:91], v[102:103], v[106:107] op_sel_hi:[1,0,1] neg_lo:[0,1,0] neg_hi:[0,1,0]
	v_cndmask_b32_e64 v110, v110, v108, s[48:49]
	ds_read_b128 v[64:67], v129 offset:12608
	ds_read_b128 v[68:71], v129 offset:12864
	ds_read_b128 v[72:75], v129 offset:13120
	ds_read_b32 v76, v131 offset:13376
	s_waitcnt lgkmcnt(6)
	v_pk_mul_f32 v[102:103], v[52:53], v[136:137]
	v_pk_mul_f32 v[108:109], v[98:99], v[54:55]
	v_pk_fma_f32 v[102:103], v[54:55], v[138:139], v[102:103]
	v_pk_fma_f32 v[108:109], v[96:97], v[52:53], v[108:109]
	v_pk_mul_f32 v[104:105], v[148:149], v[156:157] op_sel_hi:[1,0]
	v_add_f32_e32 v102, v102, v103
	v_add_f32_e32 v108, v108, v109
	v_pk_mul_f32 v[106:107], v[150:151], v[156:157] op_sel_hi:[1,0]
	v_add_f32_dpp v102, v102, v102 quad_perm:[1,0,3,2] row_mask:0xf bank_mask:0xf bound_ctrl:1
	v_pk_fma_f32 v[104:105], v[52:53], v[140:141], v[104:105]
	v_add_f32_dpp v108, v108, v108 quad_perm:[1,0,3,2] row_mask:0xf bank_mask:0xf bound_ctrl:1
	v_add_f32_dpp v102, v102, v102 quad_perm:[2,3,0,1] row_mask:0xf bank_mask:0xf bound_ctrl:1
	v_pk_fma_f32 v[106:107], v[54:55], v[142:143], v[106:107]
	v_add_f32_dpp v108, v108, v108 quad_perm:[2,3,0,1] row_mask:0xf bank_mask:0xf bound_ctrl:1
	v_add_f32_dpp v102, v102, v102 row_half_mirror row_mask:0xf bank_mask:0xf bound_ctrl:1
	ds_read_b128 v[80:83], v129 offset:13440
	v_add_f32_dpp v108, v108, v108 row_half_mirror row_mask:0xf bank_mask:0xf bound_ctrl:1
	v_add_f32_dpp v102, v102, v102 row_mirror row_mask:0xf bank_mask:0xf bound_ctrl:1
	ds_read_b128 v[84:87], v129 offset:13696
	v_add_f32_dpp v108, v108, v108 row_mirror row_mask:0xf bank_mask:0xf bound_ctrl:1
	v_pk_fma_f32 v[52:53], v[144:145], v[102:103], v[104:105] op_sel_hi:[1,0,1] neg_lo:[0,1,0] neg_hi:[0,1,0]
	v_pk_fma_f32 v[54:55], v[146:147], v[102:103], v[106:107] op_sel_hi:[1,0,1] neg_lo:[0,1,0] neg_hi:[0,1,0]
	v_cndmask_b32_e64 v110, v110, v108, s[50:51]
	ds_read_b128 v[88:91], v129 offset:13952
	ds_read_b128 v[92:95], v129 offset:14208
	ds_read_b128 v[96:99], v129 offset:14464
	ds_read_b32 v100, v131 offset:14720
	s_waitcnt vmcnt(11)
	ds_write_b128 v117, v[0:3] offset:21504
	s_waitcnt lgkmcnt(7)
	v_pk_mul_f32 v[102:103], v[52:53], v[56:57]
	v_pk_mul_f32 v[108:109], v[154:155], v[54:55]
	v_pk_fma_f32 v[102:103], v[54:55], v[58:59], v[102:103]
	v_pk_fma_f32 v[108:109], v[152:153], v[52:53], v[108:109]
	v_pk_mul_f32 v[104:105], v[68:69], v[76:77] op_sel_hi:[1,0]
	v_add_f32_e32 v102, v102, v103
	v_add_f32_e32 v108, v108, v109
	v_pk_mul_f32 v[106:107], v[70:71], v[76:77] op_sel_hi:[1,0]
	v_add_f32_dpp v102, v102, v102 quad_perm:[1,0,3,2] row_mask:0xf bank_mask:0xf bound_ctrl:1
	v_pk_fma_f32 v[104:105], v[52:53], v[60:61], v[104:105]
	v_add_f32_dpp v108, v108, v108 quad_perm:[1,0,3,2] row_mask:0xf bank_mask:0xf bound_ctrl:1
	v_add_f32_dpp v102, v102, v102 quad_perm:[2,3,0,1] row_mask:0xf bank_mask:0xf bound_ctrl:1
	v_pk_fma_f32 v[106:107], v[54:55], v[62:63], v[106:107]
	v_add_f32_dpp v108, v108, v108 quad_perm:[2,3,0,1] row_mask:0xf bank_mask:0xf bound_ctrl:1
	v_add_f32_dpp v102, v102, v102 row_half_mirror row_mask:0xf bank_mask:0xf bound_ctrl:1
	ds_read_b128 v[136:139], v129 offset:14784
	v_add_f32_dpp v108, v108, v108 row_half_mirror row_mask:0xf bank_mask:0xf bound_ctrl:1
	v_add_f32_dpp v102, v102, v102 row_mirror row_mask:0xf bank_mask:0xf bound_ctrl:1
	ds_read_b128 v[140:143], v129 offset:15040
	v_add_f32_dpp v108, v108, v108 row_mirror row_mask:0xf bank_mask:0xf bound_ctrl:1
	v_pk_fma_f32 v[52:53], v[64:65], v[102:103], v[104:105] op_sel_hi:[1,0,1] neg_lo:[0,1,0] neg_hi:[0,1,0]
	v_pk_fma_f32 v[54:55], v[66:67], v[102:103], v[106:107] op_sel_hi:[1,0,1] neg_lo:[0,1,0] neg_hi:[0,1,0]
	v_cndmask_b32_e64 v110, v110, v108, s[52:53]
	ds_read_b128 v[144:147], v129 offset:15296
	ds_read_b128 v[148:151], v129 offset:15552
	ds_read_b128 v[152:155], v129 offset:15808
	ds_read_b32 v156, v131 offset:16064
	s_waitcnt vmcnt(10)
	ds_write_b128 v119, v[4:7] offset:21504
	s_waitcnt lgkmcnt(8)
	v_pk_mul_f32 v[102:103], v[52:53], v[80:81]
	v_pk_mul_f32 v[108:109], v[74:75], v[54:55]
	v_pk_fma_f32 v[102:103], v[54:55], v[82:83], v[102:103]
	v_pk_fma_f32 v[108:109], v[72:73], v[52:53], v[108:109]
	v_pk_mul_f32 v[104:105], v[92:93], v[100:101] op_sel_hi:[1,0]
	v_add_f32_e32 v102, v102, v103
	v_add_f32_e32 v108, v108, v109
	v_pk_mul_f32 v[106:107], v[94:95], v[100:101] op_sel_hi:[1,0]
	v_add_f32_dpp v102, v102, v102 quad_perm:[1,0,3,2] row_mask:0xf bank_mask:0xf bound_ctrl:1
	v_pk_fma_f32 v[104:105], v[52:53], v[84:85], v[104:105]
	v_add_f32_dpp v108, v108, v108 quad_perm:[1,0,3,2] row_mask:0xf bank_mask:0xf bound_ctrl:1
	v_add_f32_dpp v102, v102, v102 quad_perm:[2,3,0,1] row_mask:0xf bank_mask:0xf bound_ctrl:1
	v_pk_fma_f32 v[106:107], v[54:55], v[86:87], v[106:107]
	v_add_f32_dpp v108, v108, v108 quad_perm:[2,3,0,1] row_mask:0xf bank_mask:0xf bound_ctrl:1
	v_add_f32_dpp v102, v102, v102 row_half_mirror row_mask:0xf bank_mask:0xf bound_ctrl:1
	ds_read_b128 v[56:59], v129 offset:16128
	v_add_f32_dpp v108, v108, v108 row_half_mirror row_mask:0xf bank_mask:0xf bound_ctrl:1
	v_add_f32_dpp v102, v102, v102 row_mirror row_mask:0xf bank_mask:0xf bound_ctrl:1
	ds_read_b128 v[60:63], v129 offset:16384
	v_add_f32_dpp v108, v108, v108 row_mirror row_mask:0xf bank_mask:0xf bound_ctrl:1
	v_pk_fma_f32 v[52:53], v[88:89], v[102:103], v[104:105] op_sel_hi:[1,0,1] neg_lo:[0,1,0] neg_hi:[0,1,0]
	v_pk_fma_f32 v[54:55], v[90:91], v[102:103], v[106:107] op_sel_hi:[1,0,1] neg_lo:[0,1,0] neg_hi:[0,1,0]
	v_cndmask_b32_e64 v110, v110, v108, s[54:55]
	ds_read_b128 v[64:67], v129 offset:16640
	ds_read_b128 v[68:71], v129 offset:16896
	ds_read_b128 v[72:75], v129 offset:17152
	ds_read_b32 v76, v131 offset:17408
	s_waitcnt vmcnt(9)
	ds_write_b128 v121, v[8:11] offset:21504
	s_waitcnt lgkmcnt(8)
	v_pk_mul_f32 v[102:103], v[52:53], v[136:137]
	v_pk_mul_f32 v[108:109], v[98:99], v[54:55]
	v_pk_fma_f32 v[102:103], v[54:55], v[138:139], v[102:103]
	v_pk_fma_f32 v[108:109], v[96:97], v[52:53], v[108:109]
	v_pk_mul_f32 v[104:105], v[148:149], v[156:157] op_sel_hi:[1,0]
	v_add_f32_e32 v102, v102, v103
	v_add_f32_e32 v108, v108, v109
	v_pk_mul_f32 v[106:107], v[150:151], v[156:157] op_sel_hi:[1,0]
	v_add_f32_dpp v102, v102, v102 quad_perm:[1,0,3,2] row_mask:0xf bank_mask:0xf bound_ctrl:1
	v_pk_fma_f32 v[104:105], v[52:53], v[140:141], v[104:105]
	v_add_f32_dpp v108, v108, v108 quad_perm:[1,0,3,2] row_mask:0xf bank_mask:0xf bound_ctrl:1
	v_add_f32_dpp v102, v102, v102 quad_perm:[2,3,0,1] row_mask:0xf bank_mask:0xf bound_ctrl:1
	v_pk_fma_f32 v[106:107], v[54:55], v[142:143], v[106:107]
	v_add_f32_dpp v108, v108, v108 quad_perm:[2,3,0,1] row_mask:0xf bank_mask:0xf bound_ctrl:1
	v_add_f32_dpp v102, v102, v102 row_half_mirror row_mask:0xf bank_mask:0xf bound_ctrl:1
	ds_read_b128 v[80:83], v129 offset:17472
	v_add_f32_dpp v108, v108, v108 row_half_mirror row_mask:0xf bank_mask:0xf bound_ctrl:1
	v_add_f32_dpp v102, v102, v102 row_mirror row_mask:0xf bank_mask:0xf bound_ctrl:1
	ds_read_b128 v[84:87], v129 offset:17728
	v_add_f32_dpp v108, v108, v108 row_mirror row_mask:0xf bank_mask:0xf bound_ctrl:1
	v_pk_fma_f32 v[52:53], v[144:145], v[102:103], v[104:105] op_sel_hi:[1,0,1] neg_lo:[0,1,0] neg_hi:[0,1,0]
	v_pk_fma_f32 v[54:55], v[146:147], v[102:103], v[106:107] op_sel_hi:[1,0,1] neg_lo:[0,1,0] neg_hi:[0,1,0]
	v_cndmask_b32_e64 v110, v110, v108, s[56:57]
	ds_read_b128 v[88:91], v129 offset:17984
	ds_read_b128 v[92:95], v129 offset:18240
	ds_read_b128 v[96:99], v129 offset:18496
	ds_read_b32 v100, v131 offset:18752
	s_waitcnt vmcnt(8)
	ds_write_b128 v123, v[12:15] offset:21504
	s_waitcnt lgkmcnt(8)
	v_pk_mul_f32 v[102:103], v[52:53], v[56:57]
	v_pk_mul_f32 v[108:109], v[154:155], v[54:55]
	v_pk_fma_f32 v[102:103], v[54:55], v[58:59], v[102:103]
	v_pk_fma_f32 v[108:109], v[152:153], v[52:53], v[108:109]
	v_pk_mul_f32 v[104:105], v[68:69], v[76:77] op_sel_hi:[1,0]
	v_add_f32_e32 v102, v102, v103
	v_add_f32_e32 v108, v108, v109
	v_pk_mul_f32 v[106:107], v[70:71], v[76:77] op_sel_hi:[1,0]
	v_add_f32_dpp v102, v102, v102 quad_perm:[1,0,3,2] row_mask:0xf bank_mask:0xf bound_ctrl:1
	v_pk_fma_f32 v[104:105], v[52:53], v[60:61], v[104:105]
	v_add_f32_dpp v108, v108, v108 quad_perm:[1,0,3,2] row_mask:0xf bank_mask:0xf bound_ctrl:1
	v_add_f32_dpp v102, v102, v102 quad_perm:[2,3,0,1] row_mask:0xf bank_mask:0xf bound_ctrl:1
	v_pk_fma_f32 v[106:107], v[54:55], v[62:63], v[106:107]
	v_add_f32_dpp v108, v108, v108 quad_perm:[2,3,0,1] row_mask:0xf bank_mask:0xf bound_ctrl:1
	v_add_f32_dpp v102, v102, v102 row_half_mirror row_mask:0xf bank_mask:0xf bound_ctrl:1
	ds_read_b128 v[136:139], v129 offset:18816
	v_add_f32_dpp v108, v108, v108 row_half_mirror row_mask:0xf bank_mask:0xf bound_ctrl:1
	v_add_f32_dpp v102, v102, v102 row_mirror row_mask:0xf bank_mask:0xf bound_ctrl:1
	ds_read_b128 v[140:143], v129 offset:19072
	v_add_f32_dpp v108, v108, v108 row_mirror row_mask:0xf bank_mask:0xf bound_ctrl:1
	v_pk_fma_f32 v[52:53], v[64:65], v[102:103], v[104:105] op_sel_hi:[1,0,1] neg_lo:[0,1,0] neg_hi:[0,1,0]
	v_pk_fma_f32 v[54:55], v[66:67], v[102:103], v[106:107] op_sel_hi:[1,0,1] neg_lo:[0,1,0] neg_hi:[0,1,0]
	v_cndmask_b32_e64 v110, v110, v108, s[58:59]
	ds_read_b128 v[144:147], v129 offset:19328
	ds_read_b128 v[148:151], v129 offset:19584
	ds_read_b128 v[152:155], v129 offset:19840
	ds_read_b32 v156, v131 offset:20096
	s_waitcnt vmcnt(7)
	ds_write_b128 v125, v[16:19] offset:21504
	s_waitcnt lgkmcnt(8)
	v_pk_mul_f32 v[102:103], v[52:53], v[80:81]
	v_pk_mul_f32 v[108:109], v[74:75], v[54:55]
	v_pk_fma_f32 v[102:103], v[54:55], v[82:83], v[102:103]
	v_pk_fma_f32 v[108:109], v[72:73], v[52:53], v[108:109]
	v_pk_mul_f32 v[104:105], v[92:93], v[100:101] op_sel_hi:[1,0]
	v_add_f32_e32 v102, v102, v103
	v_add_f32_e32 v108, v108, v109
	v_pk_mul_f32 v[106:107], v[94:95], v[100:101] op_sel_hi:[1,0]
	v_add_f32_dpp v102, v102, v102 quad_perm:[1,0,3,2] row_mask:0xf bank_mask:0xf bound_ctrl:1
	v_pk_fma_f32 v[104:105], v[52:53], v[84:85], v[104:105]
	v_add_f32_dpp v108, v108, v108 quad_perm:[1,0,3,2] row_mask:0xf bank_mask:0xf bound_ctrl:1
	v_add_f32_dpp v102, v102, v102 quad_perm:[2,3,0,1] row_mask:0xf bank_mask:0xf bound_ctrl:1
	v_pk_fma_f32 v[106:107], v[54:55], v[86:87], v[106:107]
	v_add_f32_dpp v108, v108, v108 quad_perm:[2,3,0,1] row_mask:0xf bank_mask:0xf bound_ctrl:1
	v_add_f32_dpp v102, v102, v102 row_half_mirror row_mask:0xf bank_mask:0xf bound_ctrl:1
	ds_read_b128 v[56:59], v129 offset:20160
	v_add_f32_dpp v108, v108, v108 row_half_mirror row_mask:0xf bank_mask:0xf bound_ctrl:1
	v_add_f32_dpp v102, v102, v102 row_mirror row_mask:0xf bank_mask:0xf bound_ctrl:1
	ds_read_b128 v[60:63], v129 offset:20416
	v_add_f32_dpp v108, v108, v108 row_mirror row_mask:0xf bank_mask:0xf bound_ctrl:1
	v_pk_fma_f32 v[52:53], v[88:89], v[102:103], v[104:105] op_sel_hi:[1,0,1] neg_lo:[0,1,0] neg_hi:[0,1,0]
	v_pk_fma_f32 v[54:55], v[90:91], v[102:103], v[106:107] op_sel_hi:[1,0,1] neg_lo:[0,1,0] neg_hi:[0,1,0]
	v_cndmask_b32_e64 v110, v110, v108, s[60:61]
	ds_read_b128 v[64:67], v129 offset:20672
	ds_read_b128 v[68:71], v129 offset:20928
	ds_read_b128 v[160:163], v129 offset:21184
	ds_read_b32 v76, v131 offset:21440
	s_waitcnt vmcnt(6)
	ds_write_b128 v127, v[20:23] offset:21504
	s_waitcnt lgkmcnt(8)
	v_pk_mul_f32 v[102:103], v[52:53], v[136:137]
	v_pk_mul_f32 v[108:109], v[98:99], v[54:55]
	v_pk_fma_f32 v[102:103], v[54:55], v[138:139], v[102:103]
	v_pk_fma_f32 v[108:109], v[96:97], v[52:53], v[108:109]
	v_pk_mul_f32 v[104:105], v[148:149], v[156:157] op_sel_hi:[1,0]
	v_add_f32_e32 v102, v102, v103
	v_add_f32_e32 v108, v108, v109
	v_pk_mul_f32 v[106:107], v[150:151], v[156:157] op_sel_hi:[1,0]
	v_add_f32_dpp v102, v102, v102 quad_perm:[1,0,3,2] row_mask:0xf bank_mask:0xf bound_ctrl:1
	v_pk_fma_f32 v[104:105], v[52:53], v[140:141], v[104:105]
	v_add_f32_dpp v108, v108, v108 quad_perm:[1,0,3,2] row_mask:0xf bank_mask:0xf bound_ctrl:1
	v_add_f32_dpp v102, v102, v102 quad_perm:[2,3,0,1] row_mask:0xf bank_mask:0xf bound_ctrl:1
	v_pk_fma_f32 v[106:107], v[54:55], v[142:143], v[106:107]
	v_add_f32_dpp v108, v108, v108 quad_perm:[2,3,0,1] row_mask:0xf bank_mask:0xf bound_ctrl:1
	v_add_f32_dpp v102, v102, v102 row_half_mirror row_mask:0xf bank_mask:0xf bound_ctrl:1
	s_nop 0
	v_add_f32_dpp v108, v108, v108 row_half_mirror row_mask:0xf bank_mask:0xf bound_ctrl:1
	v_add_f32_dpp v102, v102, v102 row_mirror row_mask:0xf bank_mask:0xf bound_ctrl:1
	s_nop 0
	v_add_f32_dpp v108, v108, v108 row_mirror row_mask:0xf bank_mask:0xf bound_ctrl:1
	v_pk_fma_f32 v[52:53], v[144:145], v[102:103], v[104:105] op_sel_hi:[1,0,1] neg_lo:[0,1,0] neg_hi:[0,1,0]
	v_pk_fma_f32 v[54:55], v[146:147], v[102:103], v[106:107] op_sel_hi:[1,0,1] neg_lo:[0,1,0] neg_hi:[0,1,0]
	v_cndmask_b32_e64 v110, v110, v108, s[62:63]
	s_waitcnt lgkmcnt(1)
	v_pk_mul_f32 v[102:103], v[52:53], v[56:57]
	v_pk_mul_f32 v[108:109], v[154:155], v[54:55]
	v_pk_fma_f32 v[102:103], v[54:55], v[58:59], v[102:103]
	v_pk_fma_f32 v[108:109], v[152:153], v[52:53], v[108:109]
	v_pk_mul_f32 v[104:105], v[68:69], v[76:77] op_sel_hi:[1,0]
	v_add_f32_e32 v102, v102, v103
	v_add_f32_e32 v108, v108, v109
	v_pk_mul_f32 v[106:107], v[70:71], v[76:77] op_sel_hi:[1,0]
	v_add_f32_dpp v102, v102, v102 quad_perm:[1,0,3,2] row_mask:0xf bank_mask:0xf bound_ctrl:1
	v_pk_fma_f32 v[104:105], v[52:53], v[60:61], v[104:105]
	v_add_f32_dpp v108, v108, v108 quad_perm:[1,0,3,2] row_mask:0xf bank_mask:0xf bound_ctrl:1
	v_add_f32_dpp v102, v102, v102 quad_perm:[2,3,0,1] row_mask:0xf bank_mask:0xf bound_ctrl:1
	v_pk_fma_f32 v[106:107], v[54:55], v[62:63], v[106:107]
	v_add_f32_dpp v108, v108, v108 quad_perm:[2,3,0,1] row_mask:0xf bank_mask:0xf bound_ctrl:1
	v_add_f32_dpp v102, v102, v102 row_half_mirror row_mask:0xf bank_mask:0xf bound_ctrl:1
	s_nop 0
	v_add_f32_dpp v108, v108, v108 row_half_mirror row_mask:0xf bank_mask:0xf bound_ctrl:1
	v_add_f32_dpp v102, v102, v102 row_mirror row_mask:0xf bank_mask:0xf bound_ctrl:1
	s_nop 0
	v_add_f32_dpp v108, v108, v108 row_mirror row_mask:0xf bank_mask:0xf bound_ctrl:1
	v_pk_fma_f32 v[52:53], v[64:65], v[102:103], v[104:105] op_sel_hi:[1,0,1] neg_lo:[0,1,0] neg_hi:[0,1,0]
	v_pk_fma_f32 v[54:55], v[66:67], v[102:103], v[106:107] op_sel_hi:[1,0,1] neg_lo:[0,1,0] neg_hi:[0,1,0]
	v_cndmask_b32_e64 v110, v110, v108, s[64:65]
	s_waitcnt lgkmcnt(0)
	s_barrier
; __device__ __forceinline__ void scan_unit(const Params p, int u, char* smem) {
;     ...
;   f32x2 sA = {0.f, 0.f}, sB = {0.f, 0.f};
;   const int jg4 = jg * 4, vi = w * 4 + rw;
	ds_read_b128 v[56:59], v129 offset:21504
	ds_read_b128 v[60:63], v129 offset:21760
	ds_read_b128 v[64:67], v129 offset:22016
	ds_read_b128 v[68:71], v129 offset:22272
	ds_read_b128 v[72:75], v129 offset:22528
	ds_read_b32 v76, v131 offset:22784
	ds_read_b128 v[80:83], v129 offset:22848
	ds_read_b128 v[84:87], v129 offset:23104
	ds_read_b128 v[88:91], v129 offset:23360
	ds_read_b128 v[92:95], v129 offset:23616
	ds_read_b128 v[96:99], v129 offset:23872
	ds_read_b32 v100, v131 offset:24128
	s_min_u32 s3, s2, 0x1fc
	s_add_i32 s3, s3, 3
	s_mul_i32 s3, s3, s0
	v_add_u32_e32 v112, s3, v168
	v_add_u32_e32 v113, s3, v116
	v_add_u32_e32 v114, s3, v118
	v_add_u32_e32 v115, s3, v120
	v_add_u32_e32 v128, s3, v122
	v_add_u32_e32 v130, s3, v124
	v_pk_mul_f32 v[108:109], v[162:163], v[54:55]
	v_pk_fma_f32 v[108:109], v[160:161], v[52:53], v[108:109]
	v_add_f32_e32 v108, v108, v109
	global_load_dwordx4 v[0:3], v112, s[96:97]
	global_load_dwordx4 v[4:7], v113, s[96:97]
	v_add_f32_dpp v108, v108, v108 quad_perm:[1,0,3,2] row_mask:0xf bank_mask:0xf bound_ctrl:1
	global_load_dwordx4 v[8:11], v114, s[96:97]
	global_load_dwordx4 v[12:15], v115, s[96:97]
	v_add_f32_dpp v108, v108, v108 quad_perm:[2,3,0,1] row_mask:0xf bank_mask:0xf bound_ctrl:1
	global_load_dwordx4 v[16:19], v128, s[96:97]
	global_load_dwordx4 v[20:23], v130, s[96:97]
	v_add_f32_dpp v108, v108, v108 row_half_mirror row_mask:0xf bank_mask:0xf bound_ctrl:1
	s_nop 0
	s_nop 0
	v_add_f32_dpp v108, v108, v108 row_mirror row_mask:0xf bank_mask:0xf bound_ctrl:1
	v_cndmask_b32_e64 v110, v110, v108, s[66:67]
	global_store_dword v132, v110, s[96:97]
	s_waitcnt lgkmcnt(6)
	v_pk_mul_f32 v[102:103], v[52:53], v[56:57]
	v_pk_fma_f32 v[102:103], v[54:55], v[58:59], v[102:103]
	v_pk_mul_f32 v[104:105], v[68:69], v[76:77] op_sel_hi:[1,0]
	v_add_f32_e32 v102, v102, v103
	v_pk_mul_f32 v[106:107], v[70:71], v[76:77] op_sel_hi:[1,0]
	ds_read_b128 v[136:139], v129 offset:24192
	v_add_f32_dpp v102, v102, v102 quad_perm:[1,0,3,2] row_mask:0xf bank_mask:0xf bound_ctrl:1
	v_pk_fma_f32 v[104:105], v[52:53], v[60:61], v[104:105]
	ds_read_b128 v[140:143], v129 offset:24448
	v_add_f32_dpp v102, v102, v102 quad_perm:[2,3,0,1] row_mask:0xf bank_mask:0xf bound_ctrl:1
	v_pk_fma_f32 v[106:107], v[54:55], v[62:63], v[106:107]
	ds_read_b128 v[144:147], v129 offset:24704
	v_add_f32_dpp v102, v102, v102 row_half_mirror row_mask:0xf bank_mask:0xf bound_ctrl:1
	ds_read_b128 v[148:151], v129 offset:24960
	ds_read_b128 v[152:155], v129 offset:25216
	v_add_f32_dpp v102, v102, v102 row_mirror row_mask:0xf bank_mask:0xf bound_ctrl:1
	v_pk_fma_f32 v[52:53], v[64:65], v[102:103], v[104:105] op_sel_hi:[1,0,1] neg_lo:[0,1,0] neg_hi:[0,1,0]
	v_pk_fma_f32 v[54:55], v[66:67], v[102:103], v[106:107] op_sel_hi:[1,0,1] neg_lo:[0,1,0] neg_hi:[0,1,0]
	ds_read_b32 v156, v131 offset:25472
	s_waitcnt lgkmcnt(6)
	v_pk_mul_f32 v[102:103], v[52:53], v[80:81]
	v_pk_mul_f32 v[108:109], v[74:75], v[54:55]
	v_pk_fma_f32 v[102:103], v[54:55], v[82:83], v[102:103]
	v_pk_fma_f32 v[108:109], v[72:73], v[52:53], v[108:109]
	v_pk_mul_f32 v[104:105], v[92:93], v[100:101] op_sel_hi:[1,0]
	v_add_f32_e32 v102, v102, v103
	v_add_f32_e32 v108, v108, v109
	v_pk_mul_f32 v[106:107], v[94:95], v[100:101] op_sel_hi:[1,0]
	v_add_f32_dpp v102, v102, v102 quad_perm:[1,0,3,2] row_mask:0xf bank_mask:0xf bound_ctrl:1
	v_pk_fma_f32 v[104:105], v[52:53], v[84:85], v[104:105]
	v_add_f32_dpp v108, v108, v108 quad_perm:[1,0,3,2] row_mask:0xf bank_mask:0xf bound_ctrl:1
	v_add_f32_dpp v102, v102, v102 quad_perm:[2,3,0,1] row_mask:0xf bank_mask:0xf bound_ctrl:1
	v_pk_fma_f32 v[106:107], v[54:55], v[86:87], v[106:107]
	v_add_f32_dpp v108, v108, v108 quad_perm:[2,3,0,1] row_mask:0xf bank_mask:0xf bound_ctrl:1
	v_add_f32_dpp v102, v102, v102 row_half_mirror row_mask:0xf bank_mask:0xf bound_ctrl:1
	ds_read_b128 v[56:59], v129 offset:25536
	v_add_f32_dpp v108, v108, v108 row_half_mirror row_mask:0xf bank_mask:0xf bound_ctrl:1
	v_add_f32_dpp v102, v102, v102 row_mirror row_mask:0xf bank_mask:0xf bound_ctrl:1
	ds_read_b128 v[60:63], v129 offset:25792
	v_add_f32_dpp v108, v108, v108 row_mirror row_mask:0xf bank_mask:0xf bound_ctrl:1
	v_pk_fma_f32 v[52:53], v[88:89], v[102:103], v[104:105] op_sel_hi:[1,0,1] neg_lo:[0,1,0] neg_hi:[0,1,0]
	v_pk_fma_f32 v[54:55], v[90:91], v[102:103], v[106:107] op_sel_hi:[1,0,1] neg_lo:[0,1,0] neg_hi:[0,1,0]
	v_cndmask_b32_e32 v110, 0, v108, vcc
	ds_read_b128 v[64:67], v129 offset:26048
	ds_read_b128 v[68:71], v129 offset:26304
	ds_read_b128 v[72:75], v129 offset:26560
	ds_read_b32 v76, v131 offset:26816
	s_waitcnt lgkmcnt(6)
	v_pk_mul_f32 v[102:103], v[52:53], v[136:137]
	v_pk_mul_f32 v[108:109], v[98:99], v[54:55]
	v_pk_fma_f32 v[102:103], v[54:55], v[138:139], v[102:103]
	v_pk_fma_f32 v[108:109], v[96:97], v[52:53], v[108:109]
	v_pk_mul_f32 v[104:105], v[148:149], v[156:157] op_sel_hi:[1,0]
	v_add_f32_e32 v102, v102, v103
	v_add_f32_e32 v108, v108, v109
	v_pk_mul_f32 v[106:107], v[150:151], v[156:157] op_sel_hi:[1,0]
	v_add_f32_dpp v102, v102, v102 quad_perm:[1,0,3,2] row_mask:0xf bank_mask:0xf bound_ctrl:1
	v_pk_fma_f32 v[104:105], v[52:53], v[140:141], v[104:105]
	v_add_f32_dpp v108, v108, v108 quad_perm:[1,0,3,2] row_mask:0xf bank_mask:0xf bound_ctrl:1
	v_add_f32_dpp v102, v102, v102 quad_perm:[2,3,0,1] row_mask:0xf bank_mask:0xf bound_ctrl:1
	v_pk_fma_f32 v[106:107], v[54:55], v[142:143], v[106:107]
	v_add_f32_dpp v108, v108, v108 quad_perm:[2,3,0,1] row_mask:0xf bank_mask:0xf bound_ctrl:1
	v_add_f32_dpp v102, v102, v102 row_half_mirror row_mask:0xf bank_mask:0xf bound_ctrl:1
	ds_read_b128 v[80:83], v129 offset:26880
	v_add_f32_dpp v108, v108, v108 row_half_mirror row_mask:0xf bank_mask:0xf bound_ctrl:1
	v_add_f32_dpp v102, v102, v102 row_mirror row_mask:0xf bank_mask:0xf bound_ctrl:1
	ds_read_b128 v[84:87], v129 offset:27136
	v_add_f32_dpp v108, v108, v108 row_mirror row_mask:0xf bank_mask:0xf bound_ctrl:1
	v_pk_fma_f32 v[52:53], v[144:145], v[102:103], v[104:105] op_sel_hi:[1,0,1] neg_lo:[0,1,0] neg_hi:[0,1,0]
	v_pk_fma_f32 v[54:55], v[146:147], v[102:103], v[106:107] op_sel_hi:[1,0,1] neg_lo:[0,1,0] neg_hi:[0,1,0]
	v_cndmask_b32_e64 v110, v110, v108, s[38:39]
	ds_read_b128 v[88:91], v129 offset:27392
	ds_read_b128 v[92:95], v129 offset:27648
	ds_read_b128 v[96:99], v129 offset:27904
	ds_read_b32 v100, v131 offset:28160
	s_waitcnt lgkmcnt(6)
	v_pk_mul_f32 v[102:103], v[52:53], v[56:57]
	v_pk_mul_f32 v[108:109], v[154:155], v[54:55]
	v_pk_fma_f32 v[102:103], v[54:55], v[58:59], v[102:103]
	v_pk_fma_f32 v[108:109], v[152:153], v[52:53], v[108:109]
	v_pk_mul_f32 v[104:105], v[68:69], v[76:77] op_sel_hi:[1,0]
	v_add_f32_e32 v102, v102, v103
	v_add_f32_e32 v108, v108, v109
	v_pk_mul_f32 v[106:107], v[70:71], v[76:77] op_sel_hi:[1,0]
	v_add_f32_dpp v102, v102, v102 quad_perm:[1,0,3,2] row_mask:0xf bank_mask:0xf bound_ctrl:1
	v_pk_fma_f32 v[104:105], v[52:53], v[60:61], v[104:105]
	v_add_f32_dpp v108, v108, v108 quad_perm:[1,0,3,2] row_mask:0xf bank_mask:0xf bound_ctrl:1
	v_add_f32_dpp v102, v102, v102 quad_perm:[2,3,0,1] row_mask:0xf bank_mask:0xf bound_ctrl:1
	v_pk_fma_f32 v[106:107], v[54:55], v[62:63], v[106:107]
	v_add_f32_dpp v108, v108, v108 quad_perm:[2,3,0,1] row_mask:0xf bank_mask:0xf bound_ctrl:1
	v_add_f32_dpp v102, v102, v102 row_half_mirror row_mask:0xf bank_mask:0xf bound_ctrl:1
	ds_read_b128 v[136:139], v129 offset:28224
	v_add_f32_dpp v108, v108, v108 row_half_mirror row_mask:0xf bank_mask:0xf bound_ctrl:1
	v_add_f32_dpp v102, v102, v102 row_mirror row_mask:0xf bank_mask:0xf bound_ctrl:1
	ds_read_b128 v[140:143], v129 offset:28480
	v_add_f32_dpp v108, v108, v108 row_mirror row_mask:0xf bank_mask:0xf bound_ctrl:1
	v_pk_fma_f32 v[52:53], v[64:65], v[102:103], v[104:105] op_sel_hi:[1,0,1] neg_lo:[0,1,0] neg_hi:[0,1,0]
	v_pk_fma_f32 v[54:55], v[66:67], v[102:103], v[106:107] op_sel_hi:[1,0,1] neg_lo:[0,1,0] neg_hi:[0,1,0]
	v_cndmask_b32_e64 v110, v110, v108, s[40:41]
	ds_read_b128 v[144:147], v129 offset:28736
	ds_read_b128 v[148:151], v129 offset:28992
	ds_read_b128 v[152:155], v129 offset:29248
	ds_read_b32 v156, v131 offset:29504
	s_waitcnt lgkmcnt(6)
	v_pk_mul_f32 v[102:103], v[52:53], v[80:81]
	v_pk_mul_f32 v[108:109], v[74:75], v[54:55]
	v_pk_fma_f32 v[102:103], v[54:55], v[82:83], v[102:103]
	v_pk_fma_f32 v[108:109], v[72:73], v[52:53], v[108:109]
	v_pk_mul_f32 v[104:105], v[92:93], v[100:101] op_sel_hi:[1,0]
	v_add_f32_e32 v102, v102, v103
	v_add_f32_e32 v108, v108, v109
	v_pk_mul_f32 v[106:107], v[94:95], v[100:101] op_sel_hi:[1,0]
	v_add_f32_dpp v102, v102, v102 quad_perm:[1,0,3,2] row_mask:0xf bank_mask:0xf bound_ctrl:1
	v_pk_fma_f32 v[104:105], v[52:53], v[84:85], v[104:105]
	v_add_f32_dpp v108, v108, v108 quad_perm:[1,0,3,2] row_mask:0xf bank_mask:0xf bound_ctrl:1
	v_add_f32_dpp v102, v102, v102 quad_perm:[2,3,0,1] row_mask:0xf bank_mask:0xf bound_ctrl:1
	v_pk_fma_f32 v[106:107], v[54:55], v[86:87], v[106:107]
	v_add_f32_dpp v108, v108, v108 quad_perm:[2,3,0,1] row_mask:0xf bank_mask:0xf bound_ctrl:1
	v_add_f32_dpp v102, v102, v102 row_half_mirror row_mask:0xf bank_mask:0xf bound_ctrl:1
	ds_read_b128 v[56:59], v129 offset:29568
	v_add_f32_dpp v108, v108, v108 row_half_mirror row_mask:0xf bank_mask:0xf bound_ctrl:1
	v_add_f32_dpp v102, v102, v102 row_mirror row_mask:0xf bank_mask:0xf bound_ctrl:1
	ds_read_b128 v[60:63], v129 offset:29824
	v_add_f32_dpp v108, v108, v108 row_mirror row_mask:0xf bank_mask:0xf bound_ctrl:1
	v_pk_fma_f32 v[52:53], v[88:89], v[102:103], v[104:105] op_sel_hi:[1,0,1] neg_lo:[0,1,0] neg_hi:[0,1,0]
	v_pk_fma_f32 v[54:55], v[90:91], v[102:103], v[106:107] op_sel_hi:[1,0,1] neg_lo:[0,1,0] neg_hi:[0,1,0]
	v_cndmask_b32_e64 v110, v110, v108, s[42:43]
	ds_read_b128 v[64:67], v129 offset:30080
	ds_read_b128 v[68:71], v129 offset:30336
	ds_read_b128 v[72:75], v129 offset:30592
	ds_read_b32 v76, v131 offset:30848
	s_waitcnt lgkmcnt(6)
	v_pk_mul_f32 v[102:103], v[52:53], v[136:137]
	v_pk_mul_f32 v[108:109], v[98:99], v[54:55]
	v_pk_fma_f32 v[102:103], v[54:55], v[138:139], v[102:103]
	v_pk_fma_f32 v[108:109], v[96:97], v[52:53], v[108:109]
	v_pk_mul_f32 v[104:105], v[148:149], v[156:157] op_sel_hi:[1,0]
	v_add_f32_e32 v102, v102, v103
	v_add_f32_e32 v108, v108, v109
	v_pk_mul_f32 v[106:107], v[150:151], v[156:157] op_sel_hi:[1,0]
	v_add_f32_dpp v102, v102, v102 quad_perm:[1,0,3,2] row_mask:0xf bank_mask:0xf bound_ctrl:1
	v_pk_fma_f32 v[104:105], v[52:53], v[140:141], v[104:105]
	v_add_f32_dpp v108, v108, v108 quad_perm:[1,0,3,2] row_mask:0xf bank_mask:0xf bound_ctrl:1
	v_add_f32_dpp v102, v102, v102 quad_perm:[2,3,0,1] row_mask:0xf bank_mask:0xf bound_ctrl:1
	v_pk_fma_f32 v[106:107], v[54:55], v[142:143], v[106:107]
	v_add_f32_dpp v108, v108, v108 quad_perm:[2,3,0,1] row_mask:0xf bank_mask:0xf bound_ctrl:1
	v_add_f32_dpp v102, v102, v102 row_half_mirror row_mask:0xf bank_mask:0xf bound_ctrl:1
	ds_read_b128 v[80:83], v129 offset:30912
	v_add_f32_dpp v108, v108, v108 row_half_mirror row_mask:0xf bank_mask:0xf bound_ctrl:1
	v_add_f32_dpp v102, v102, v102 row_mirror row_mask:0xf bank_mask:0xf bound_ctrl:1
	ds_read_b128 v[84:87], v129 offset:31168
	v_add_f32_dpp v108, v108, v108 row_mirror row_mask:0xf bank_mask:0xf bound_ctrl:1
	v_pk_fma_f32 v[52:53], v[144:145], v[102:103], v[104:105] op_sel_hi:[1,0,1] neg_lo:[0,1,0] neg_hi:[0,1,0]
	v_pk_fma_f32 v[54:55], v[146:147], v[102:103], v[106:107] op_sel_hi:[1,0,1] neg_lo:[0,1,0] neg_hi:[0,1,0]
	v_cndmask_b32_e64 v110, v110, v108, s[44:45]
	ds_read_b128 v[88:91], v129 offset:31424
	ds_read_b128 v[92:95], v129 offset:31680
	ds_read_b128 v[96:99], v129 offset:31936
	ds_read_b32 v100, v131 offset:32192
	s_waitcnt lgkmcnt(6)
	v_pk_mul_f32 v[102:103], v[52:53], v[56:57]
	v_pk_mul_f32 v[108:109], v[154:155], v[54:55]
	v_pk_fma_f32 v[102:103], v[54:55], v[58:59], v[102:103]
	v_pk_fma_f32 v[108:109], v[152:153], v[52:53], v[108:109]
	v_pk_mul_f32 v[104:105], v[68:69], v[76:77] op_sel_hi:[1,0]
	v_add_f32_e32 v102, v102, v103
	v_add_f32_e32 v108, v108, v109
	v_pk_mul_f32 v[106:107], v[70:71], v[76:77] op_sel_hi:[1,0]
	v_add_f32_dpp v102, v102, v102 quad_perm:[1,0,3,2] row_mask:0xf bank_mask:0xf bound_ctrl:1
	v_pk_fma_f32 v[104:105], v[52:53], v[60:61], v[104:105]
	v_add_f32_dpp v108, v108, v108 quad_perm:[1,0,3,2] row_mask:0xf bank_mask:0xf bound_ctrl:1
	v_add_f32_dpp v102, v102, v102 quad_perm:[2,3,0,1] row_mask:0xf bank_mask:0xf bound_ctrl:1
	v_pk_fma_f32 v[106:107], v[54:55], v[62:63], v[106:107]
	v_add_f32_dpp v108, v108, v108 quad_perm:[2,3,0,1] row_mask:0xf bank_mask:0xf bound_ctrl:1
	v_add_f32_dpp v102, v102, v102 row_half_mirror row_mask:0xf bank_mask:0xf bound_ctrl:1
	ds_read_b128 v[136:139], v129 offset:32256
	v_add_f32_dpp v108, v108, v108 row_half_mirror row_mask:0xf bank_mask:0xf bound_ctrl:1
	v_add_f32_dpp v102, v102, v102 row_mirror row_mask:0xf bank_mask:0xf bound_ctrl:1
	ds_read_b128 v[140:143], v129 offset:32512
	v_add_f32_dpp v108, v108, v108 row_mirror row_mask:0xf bank_mask:0xf bound_ctrl:1
	v_pk_fma_f32 v[52:53], v[64:65], v[102:103], v[104:105] op_sel_hi:[1,0,1] neg_lo:[0,1,0] neg_hi:[0,1,0]
	v_pk_fma_f32 v[54:55], v[66:67], v[102:103], v[106:107] op_sel_hi:[1,0,1] neg_lo:[0,1,0] neg_hi:[0,1,0]
	v_cndmask_b32_e64 v110, v110, v108, s[46:47]
	ds_read_b128 v[144:147], v129 offset:32768
	ds_read_b128 v[148:151], v129 offset:33024
	ds_read_b128 v[152:155], v129 offset:33280
	ds_read_b32 v156, v131 offset:33536
	s_waitcnt lgkmcnt(6)
	v_pk_mul_f32 v[102:103], v[52:53], v[80:81]
	v_pk_mul_f32 v[108:109], v[74:75], v[54:55]
	v_pk_fma_f32 v[102:103], v[54:55], v[82:83], v[102:103]
	v_pk_fma_f32 v[108:109], v[72:73], v[52:53], v[108:109]
	v_pk_mul_f32 v[104:105], v[92:93], v[100:101] op_sel_hi:[1,0]
	v_add_f32_e32 v102, v102, v103
	v_add_f32_e32 v108, v108, v109
	v_pk_mul_f32 v[106:107], v[94:95], v[100:101] op_sel_hi:[1,0]
	v_add_f32_dpp v102, v102, v102 quad_perm:[1,0,3,2] row_mask:0xf bank_mask:0xf bound_ctrl:1
	v_pk_fma_f32 v[104:105], v[52:53], v[84:85], v[104:105]
	v_add_f32_dpp v108, v108, v108 quad_perm:[1,0,3,2] row_mask:0xf bank_mask:0xf bound_ctrl:1
	v_add_f32_dpp v102, v102, v102 quad_perm:[2,3,0,1] row_mask:0xf bank_mask:0xf bound_ctrl:1
	v_pk_fma_f32 v[106:107], v[54:55], v[86:87], v[106:107]
	v_add_f32_dpp v108, v108, v108 quad_perm:[2,3,0,1] row_mask:0xf bank_mask:0xf bound_ctrl:1
	v_add_f32_dpp v102, v102, v102 row_half_mirror row_mask:0xf bank_mask:0xf bound_ctrl:1
	ds_read_b128 v[56:59], v129 offset:33600
	v_add_f32_dpp v108, v108, v108 row_half_mirror row_mask:0xf bank_mask:0xf bound_ctrl:1
	v_add_f32_dpp v102, v102, v102 row_mirror row_mask:0xf bank_mask:0xf bound_ctrl:1
	ds_read_b128 v[60:63], v129 offset:33856
	v_add_f32_dpp v108, v108, v108 row_mirror row_mask:0xf bank_mask:0xf bound_ctrl:1
	v_pk_fma_f32 v[52:53], v[88:89], v[102:103], v[104:105] op_sel_hi:[1,0,1] neg_lo:[0,1,0] neg_hi:[0,1,0]
	v_pk_fma_f32 v[54:55], v[90:91], v[102:103], v[106:107] op_sel_hi:[1,0,1] neg_lo:[0,1,0] neg_hi:[0,1,0]
	v_cndmask_b32_e64 v110, v110, v108, s[48:49]
	ds_read_b128 v[64:67], v129 offset:34112
	ds_read_b128 v[68:71], v129 offset:34368
	ds_read_b128 v[72:75], v129 offset:34624
	ds_read_b32 v76, v131 offset:34880
	s_waitcnt lgkmcnt(6)
	v_pk_mul_f32 v[102:103], v[52:53], v[136:137]
	v_pk_mul_f32 v[108:109], v[98:99], v[54:55]
	v_pk_fma_f32 v[102:103], v[54:55], v[138:139], v[102:103]
	v_pk_fma_f32 v[108:109], v[96:97], v[52:53], v[108:109]
	v_pk_mul_f32 v[104:105], v[148:149], v[156:157] op_sel_hi:[1,0]
	v_add_f32_e32 v102, v102, v103
	v_add_f32_e32 v108, v108, v109
	v_pk_mul_f32 v[106:107], v[150:151], v[156:157] op_sel_hi:[1,0]
	v_add_f32_dpp v102, v102, v102 quad_perm:[1,0,3,2] row_mask:0xf bank_mask:0xf bound_ctrl:1
	v_pk_fma_f32 v[104:105], v[52:53], v[140:141], v[104:105]
	v_add_f32_dpp v108, v108, v108 quad_perm:[1,0,3,2] row_mask:0xf bank_mask:0xf bound_ctrl:1
	v_add_f32_dpp v102, v102, v102 quad_perm:[2,3,0,1] row_mask:0xf bank_mask:0xf bound_ctrl:1
	v_pk_fma_f32 v[106:107], v[54:55], v[142:143], v[106:107]
	v_add_f32_dpp v108, v108, v108 quad_perm:[2,3,0,1] row_mask:0xf bank_mask:0xf bound_ctrl:1
	v_add_f32_dpp v102, v102, v102 row_half_mirror row_mask:0xf bank_mask:0xf bound_ctrl:1
	ds_read_b128 v[80:83], v129 offset:34944
	v_add_f32_dpp v108, v108, v108 row_half_mirror row_mask:0xf bank_mask:0xf bound_ctrl:1
	v_add_f32_dpp v102, v102, v102 row_mirror row_mask:0xf bank_mask:0xf bound_ctrl:1
	ds_read_b128 v[84:87], v129 offset:35200
	v_add_f32_dpp v108, v108, v108 row_mirror row_mask:0xf bank_mask:0xf bound_ctrl:1
	v_pk_fma_f32 v[52:53], v[144:145], v[102:103], v[104:105] op_sel_hi:[1,0,1] neg_lo:[0,1,0] neg_hi:[0,1,0]
	v_pk_fma_f32 v[54:55], v[146:147], v[102:103], v[106:107] op_sel_hi:[1,0,1] neg_lo:[0,1,0] neg_hi:[0,1,0]
	v_cndmask_b32_e64 v110, v110, v108, s[50:51]
	ds_read_b128 v[88:91], v129 offset:35456
	ds_read_b128 v[92:95], v129 offset:35712
	ds_read_b128 v[96:99], v129 offset:35968
	ds_read_b32 v100, v131 offset:36224
	s_waitcnt vmcnt(11)
	ds_write_b128 v117, v[28:31]
	s_waitcnt lgkmcnt(7)
	v_pk_mul_f32 v[102:103], v[52:53], v[56:57]
	v_pk_mul_f32 v[108:109], v[154:155], v[54:55]
	v_pk_fma_f32 v[102:103], v[54:55], v[58:59], v[102:103]
	v_pk_fma_f32 v[108:109], v[152:153], v[52:53], v[108:109]
	v_pk_mul_f32 v[104:105], v[68:69], v[76:77] op_sel_hi:[1,0]
	v_add_f32_e32 v102, v102, v103
	v_add_f32_e32 v108, v108, v109
	v_pk_mul_f32 v[106:107], v[70:71], v[76:77] op_sel_hi:[1,0]
	v_add_f32_dpp v102, v102, v102 quad_perm:[1,0,3,2] row_mask:0xf bank_mask:0xf bound_ctrl:1
	v_pk_fma_f32 v[104:105], v[52:53], v[60:61], v[104:105]
	v_add_f32_dpp v108, v108, v108 quad_perm:[1,0,3,2] row_mask:0xf bank_mask:0xf bound_ctrl:1
	v_add_f32_dpp v102, v102, v102 quad_perm:[2,3,0,1] row_mask:0xf bank_mask:0xf bound_ctrl:1
	v_pk_fma_f32 v[106:107], v[54:55], v[62:63], v[106:107]
	v_add_f32_dpp v108, v108, v108 quad_perm:[2,3,0,1] row_mask:0xf bank_mask:0xf bound_ctrl:1
	v_add_f32_dpp v102, v102, v102 row_half_mirror row_mask:0xf bank_mask:0xf bound_ctrl:1
	ds_read_b128 v[136:139], v129 offset:36288
	v_add_f32_dpp v108, v108, v108 row_half_mirror row_mask:0xf bank_mask:0xf bound_ctrl:1
	v_add_f32_dpp v102, v102, v102 row_mirror row_mask:0xf bank_mask:0xf bound_ctrl:1
	ds_read_b128 v[140:143], v129 offset:36544
	v_add_f32_dpp v108, v108, v108 row_mirror row_mask:0xf bank_mask:0xf bound_ctrl:1
	v_pk_fma_f32 v[52:53], v[64:65], v[102:103], v[104:105] op_sel_hi:[1,0,1] neg_lo:[0,1,0] neg_hi:[0,1,0]
	v_pk_fma_f32 v[54:55], v[66:67], v[102:103], v[106:107] op_sel_hi:[1,0,1] neg_lo:[0,1,0] neg_hi:[0,1,0]
	v_cndmask_b32_e64 v110, v110, v108, s[52:53]
	ds_read_b128 v[144:147], v129 offset:36800
	ds_read_b128 v[148:151], v129 offset:37056
	ds_read_b128 v[152:155], v129 offset:37312
	ds_read_b32 v156, v131 offset:37568
	s_waitcnt vmcnt(10)
	ds_write_b128 v119, v[32:35]
	s_waitcnt lgkmcnt(8)
	v_pk_mul_f32 v[102:103], v[52:53], v[80:81]
	v_pk_mul_f32 v[108:109], v[74:75], v[54:55]
	v_pk_fma_f32 v[102:103], v[54:55], v[82:83], v[102:103]
	v_pk_fma_f32 v[108:109], v[72:73], v[52:53], v[108:109]
	v_pk_mul_f32 v[104:105], v[92:93], v[100:101] op_sel_hi:[1,0]
	v_add_f32_e32 v102, v102, v103
	v_add_f32_e32 v108, v108, v109
	v_pk_mul_f32 v[106:107], v[94:95], v[100:101] op_sel_hi:[1,0]
	v_add_f32_dpp v102, v102, v102 quad_perm:[1,0,3,2] row_mask:0xf bank_mask:0xf bound_ctrl:1
	v_pk_fma_f32 v[104:105], v[52:53], v[84:85], v[104:105]
	v_add_f32_dpp v108, v108, v108 quad_perm:[1,0,3,2] row_mask:0xf bank_mask:0xf bound_ctrl:1
	v_add_f32_dpp v102, v102, v102 quad_perm:[2,3,0,1] row_mask:0xf bank_mask:0xf bound_ctrl:1
	v_pk_fma_f32 v[106:107], v[54:55], v[86:87], v[106:107]
	v_add_f32_dpp v108, v108, v108 quad_perm:[2,3,0,1] row_mask:0xf bank_mask:0xf bound_ctrl:1
	v_add_f32_dpp v102, v102, v102 row_half_mirror row_mask:0xf bank_mask:0xf bound_ctrl:1
	ds_read_b128 v[56:59], v129 offset:37632
	v_add_f32_dpp v108, v108, v108 row_half_mirror row_mask:0xf bank_mask:0xf bound_ctrl:1
	v_add_f32_dpp v102, v102, v102 row_mirror row_mask:0xf bank_mask:0xf bound_ctrl:1
	ds_read_b128 v[60:63], v129 offset:37888
	v_add_f32_dpp v108, v108, v108 row_mirror row_mask:0xf bank_mask:0xf bound_ctrl:1
	v_pk_fma_f32 v[52:53], v[88:89], v[102:103], v[104:105] op_sel_hi:[1,0,1] neg_lo:[0,1,0] neg_hi:[0,1,0]
	v_pk_fma_f32 v[54:55], v[90:91], v[102:103], v[106:107] op_sel_hi:[1,0,1] neg_lo:[0,1,0] neg_hi:[0,1,0]
	v_cndmask_b32_e64 v110, v110, v108, s[54:55]
	ds_read_b128 v[64:67], v129 offset:38144
	ds_read_b128 v[68:71], v129 offset:38400
	ds_read_b128 v[72:75], v129 offset:38656
	ds_read_b32 v76, v131 offset:38912
	s_waitcnt vmcnt(9)
	ds_write_b128 v121, v[36:39]
	s_waitcnt lgkmcnt(8)
	v_pk_mul_f32 v[102:103], v[52:53], v[136:137]
	v_pk_mul_f32 v[108:109], v[98:99], v[54:55]
	v_pk_fma_f32 v[102:103], v[54:55], v[138:139], v[102:103]
	v_pk_fma_f32 v[108:109], v[96:97], v[52:53], v[108:109]
	v_pk_mul_f32 v[104:105], v[148:149], v[156:157] op_sel_hi:[1,0]
	v_add_f32_e32 v102, v102, v103
	v_add_f32_e32 v108, v108, v109
	v_pk_mul_f32 v[106:107], v[150:151], v[156:157] op_sel_hi:[1,0]
	v_add_f32_dpp v102, v102, v102 quad_perm:[1,0,3,2] row_mask:0xf bank_mask:0xf bound_ctrl:1
	v_pk_fma_f32 v[104:105], v[52:53], v[140:141], v[104:105]
	v_add_f32_dpp v108, v108, v108 quad_perm:[1,0,3,2] row_mask:0xf bank_mask:0xf bound_ctrl:1
	v_add_f32_dpp v102, v102, v102 quad_perm:[2,3,0,1] row_mask:0xf bank_mask:0xf bound_ctrl:1
	v_pk_fma_f32 v[106:107], v[54:55], v[142:143], v[106:107]
	v_add_f32_dpp v108, v108, v108 quad_perm:[2,3,0,1] row_mask:0xf bank_mask:0xf bound_ctrl:1
	v_add_f32_dpp v102, v102, v102 row_half_mirror row_mask:0xf bank_mask:0xf bound_ctrl:1
	ds_read_b128 v[80:83], v129 offset:38976
	v_add_f32_dpp v108, v108, v108 row_half_mirror row_mask:0xf bank_mask:0xf bound_ctrl:1
	v_add_f32_dpp v102, v102, v102 row_mirror row_mask:0xf bank_mask:0xf bound_ctrl:1
	ds_read_b128 v[84:87], v129 offset:39232
	v_add_f32_dpp v108, v108, v108 row_mirror row_mask:0xf bank_mask:0xf bound_ctrl:1
	v_pk_fma_f32 v[52:53], v[144:145], v[102:103], v[104:105] op_sel_hi:[1,0,1] neg_lo:[0,1,0] neg_hi:[0,1,0]
	v_pk_fma_f32 v[54:55], v[146:147], v[102:103], v[106:107] op_sel_hi:[1,0,1] neg_lo:[0,1,0] neg_hi:[0,1,0]
	v_cndmask_b32_e64 v110, v110, v108, s[56:57]
	ds_read_b128 v[88:91], v129 offset:39488
	ds_read_b128 v[92:95], v129 offset:39744
	ds_read_b128 v[96:99], v129 offset:40000
	ds_read_b32 v100, v131 offset:40256
	s_waitcnt vmcnt(8)
	ds_write_b128 v123, v[40:43]
	s_waitcnt lgkmcnt(8)
; #define LBAR() asm volatile("s_waitcnt lgkmcnt(0)\n\ts_barrier" ::: "memory")
; #define SC_STORE(R, B)                                                \
;   _Pragma("unroll") for (int i = 0; i < 6; ++i) *(f32x4*)(buf + (B) * SC_CH * SC_STEPF + pf[i]) = R[i];
; __device__ __forceinline__ void scan_unit(const Params p, int u, char* smem) {
;     ...
;   __syncthreads();
;   __builtin_amdgcn_s_setprio(3);
;   SC_LOAD(lregA, 0);
;   SC_STORE(lregA, 0);
;   SC_LOAD(lregB, 1);
;   __syncthreads();
;   for (int c = 0; c < nch; c += 2) {
;     SC_LOAD(lregA, c + 2);
;     SC_COMPUTE(c, 0);
;     SC_STORE(lregB, 1);
;     LBAR();
;     SC_LOAD(lregB, c + 3);
;     SC_COMPUTE(c + 1, 1);
;     SC_STORE(lregA, 0);
;     LBAR();
;   }
	v_pk_mul_f32 v[102:103], v[52:53], v[56:57]
	v_pk_mul_f32 v[108:109], v[154:155], v[54:55]
	v_pk_fma_f32 v[102:103], v[54:55], v[58:59], v[102:103]
	v_pk_fma_f32 v[108:109], v[152:153], v[52:53], v[108:109]
	v_pk_mul_f32 v[104:105], v[68:69], v[76:77] op_sel_hi:[1,0]
	v_add_f32_e32 v102, v102, v103
	v_add_f32_e32 v108, v108, v109
	v_pk_mul_f32 v[106:107], v[70:71], v[76:77] op_sel_hi:[1,0]
	v_add_f32_dpp v102, v102, v102 quad_perm:[1,0,3,2] row_mask:0xf bank_mask:0xf bound_ctrl:1
	v_pk_fma_f32 v[104:105], v[52:53], v[60:61], v[104:105]
	v_add_f32_dpp v108, v108, v108 quad_perm:[1,0,3,2] row_mask:0xf bank_mask:0xf bound_ctrl:1
	v_add_f32_dpp v102, v102, v102 quad_perm:[2,3,0,1] row_mask:0xf bank_mask:0xf bound_ctrl:1
	v_pk_fma_f32 v[106:107], v[54:55], v[62:63], v[106:107]
	v_add_f32_dpp v108, v108, v108 quad_perm:[2,3,0,1] row_mask:0xf bank_mask:0xf bound_ctrl:1
	v_add_f32_dpp v102, v102, v102 row_half_mirror row_mask:0xf bank_mask:0xf bound_ctrl:1
	ds_read_b128 v[136:139], v129 offset:40320
	v_add_f32_dpp v108, v108, v108 row_half_mirror row_mask:0xf bank_mask:0xf bound_ctrl:1
	v_add_f32_dpp v102, v102, v102 row_mirror row_mask:0xf bank_mask:0xf bound_ctrl:1
	ds_read_b128 v[140:143], v129 offset:40576
	v_add_f32_dpp v108, v108, v108 row_mirror row_mask:0xf bank_mask:0xf bound_ctrl:1
	v_pk_fma_f32 v[52:53], v[64:65], v[102:103], v[104:105] op_sel_hi:[1,0,1] neg_lo:[0,1,0] neg_hi:[0,1,0]
	v_pk_fma_f32 v[54:55], v[66:67], v[102:103], v[106:107] op_sel_hi:[1,0,1] neg_lo:[0,1,0] neg_hi:[0,1,0]
	v_cndmask_b32_e64 v110, v110, v108, s[58:59]
	ds_read_b128 v[144:147], v129 offset:40832
	ds_read_b128 v[148:151], v129 offset:41088
	ds_read_b128 v[152:155], v129 offset:41344
	ds_read_b32 v156, v131 offset:41600
	s_waitcnt vmcnt(7)
	ds_write_b128 v125, v[44:47]
	s_waitcnt lgkmcnt(8)
	v_pk_mul_f32 v[102:103], v[52:53], v[80:81]
	v_pk_mul_f32 v[108:109], v[74:75], v[54:55]
	v_pk_fma_f32 v[102:103], v[54:55], v[82:83], v[102:103]
	v_pk_fma_f32 v[108:109], v[72:73], v[52:53], v[108:109]
	v_pk_mul_f32 v[104:105], v[92:93], v[100:101] op_sel_hi:[1,0]
	v_add_f32_e32 v102, v102, v103
	v_add_f32_e32 v108, v108, v109
	v_pk_mul_f32 v[106:107], v[94:95], v[100:101] op_sel_hi:[1,0]
	v_add_f32_dpp v102, v102, v102 quad_perm:[1,0,3,2] row_mask:0xf bank_mask:0xf bound_ctrl:1
	v_pk_fma_f32 v[104:105], v[52:53], v[84:85], v[104:105]
	v_add_f32_dpp v108, v108, v108 quad_perm:[1,0,3,2] row_mask:0xf bank_mask:0xf bound_ctrl:1
	v_add_f32_dpp v102, v102, v102 quad_perm:[2,3,0,1] row_mask:0xf bank_mask:0xf bound_ctrl:1
	v_pk_fma_f32 v[106:107], v[54:55], v[86:87], v[106:107]
	v_add_f32_dpp v108, v108, v108 quad_perm:[2,3,0,1] row_mask:0xf bank_mask:0xf bound_ctrl:1
	v_add_f32_dpp v102, v102, v102 row_half_mirror row_mask:0xf bank_mask:0xf bound_ctrl:1
	ds_read_b128 v[56:59], v129 offset:41664
	v_add_f32_dpp v108, v108, v108 row_half_mirror row_mask:0xf bank_mask:0xf bound_ctrl:1
	v_add_f32_dpp v102, v102, v102 row_mirror row_mask:0xf bank_mask:0xf bound_ctrl:1
	ds_read_b128 v[60:63], v129 offset:41920
	v_add_f32_dpp v108, v108, v108 row_mirror row_mask:0xf bank_mask:0xf bound_ctrl:1
	v_pk_fma_f32 v[52:53], v[88:89], v[102:103], v[104:105] op_sel_hi:[1,0,1] neg_lo:[0,1,0] neg_hi:[0,1,0]
	v_pk_fma_f32 v[54:55], v[90:91], v[102:103], v[106:107] op_sel_hi:[1,0,1] neg_lo:[0,1,0] neg_hi:[0,1,0]
	v_cndmask_b32_e64 v110, v110, v108, s[60:61]
	ds_read_b128 v[64:67], v129 offset:42176
	ds_read_b128 v[68:71], v129 offset:42432
	ds_read_b128 v[160:163], v129 offset:42688
	ds_read_b32 v76, v131 offset:42944
	s_waitcnt vmcnt(6)
	ds_write_b128 v127, v[24:27]
	s_waitcnt lgkmcnt(8)
	v_pk_mul_f32 v[102:103], v[52:53], v[136:137]
	v_pk_mul_f32 v[108:109], v[98:99], v[54:55]
	v_pk_fma_f32 v[102:103], v[54:55], v[138:139], v[102:103]
	v_pk_fma_f32 v[108:109], v[96:97], v[52:53], v[108:109]
	v_pk_mul_f32 v[104:105], v[148:149], v[156:157] op_sel_hi:[1,0]
	v_add_f32_e32 v102, v102, v103
	v_add_f32_e32 v108, v108, v109
	v_pk_mul_f32 v[106:107], v[150:151], v[156:157] op_sel_hi:[1,0]
	v_add_f32_dpp v102, v102, v102 quad_perm:[1,0,3,2] row_mask:0xf bank_mask:0xf bound_ctrl:1
	v_pk_fma_f32 v[104:105], v[52:53], v[140:141], v[104:105]
	v_add_f32_dpp v108, v108, v108 quad_perm:[1,0,3,2] row_mask:0xf bank_mask:0xf bound_ctrl:1
	v_add_f32_dpp v102, v102, v102 quad_perm:[2,3,0,1] row_mask:0xf bank_mask:0xf bound_ctrl:1
	v_pk_fma_f32 v[106:107], v[54:55], v[142:143], v[106:107]
	v_add_f32_dpp v108, v108, v108 quad_perm:[2,3,0,1] row_mask:0xf bank_mask:0xf bound_ctrl:1
	v_add_f32_dpp v102, v102, v102 row_half_mirror row_mask:0xf bank_mask:0xf bound_ctrl:1
	s_nop 0
	v_add_f32_dpp v108, v108, v108 row_half_mirror row_mask:0xf bank_mask:0xf bound_ctrl:1
	v_add_f32_dpp v102, v102, v102 row_mirror row_mask:0xf bank_mask:0xf bound_ctrl:1
	s_nop 0
	v_add_f32_dpp v108, v108, v108 row_mirror row_mask:0xf bank_mask:0xf bound_ctrl:1
	v_pk_fma_f32 v[52:53], v[144:145], v[102:103], v[104:105] op_sel_hi:[1,0,1] neg_lo:[0,1,0] neg_hi:[0,1,0]
	v_pk_fma_f32 v[54:55], v[146:147], v[102:103], v[106:107] op_sel_hi:[1,0,1] neg_lo:[0,1,0] neg_hi:[0,1,0]
	v_cndmask_b32_e64 v110, v110, v108, s[62:63]
	s_waitcnt lgkmcnt(1)
	v_pk_mul_f32 v[102:103], v[52:53], v[56:57]
	v_pk_mul_f32 v[108:109], v[154:155], v[54:55]
	v_pk_fma_f32 v[102:103], v[54:55], v[58:59], v[102:103]
	v_pk_fma_f32 v[108:109], v[152:153], v[52:53], v[108:109]
	v_pk_mul_f32 v[104:105], v[68:69], v[76:77] op_sel_hi:[1,0]
	v_add_f32_e32 v102, v102, v103
	v_add_f32_e32 v108, v108, v109
	v_pk_mul_f32 v[106:107], v[70:71], v[76:77] op_sel_hi:[1,0]
	v_add_f32_dpp v102, v102, v102 quad_perm:[1,0,3,2] row_mask:0xf bank_mask:0xf bound_ctrl:1
	v_pk_fma_f32 v[104:105], v[52:53], v[60:61], v[104:105]
	v_add_f32_dpp v108, v108, v108 quad_perm:[1,0,3,2] row_mask:0xf bank_mask:0xf bound_ctrl:1
	v_add_f32_dpp v102, v102, v102 quad_perm:[2,3,0,1] row_mask:0xf bank_mask:0xf bound_ctrl:1
	v_pk_fma_f32 v[106:107], v[54:55], v[62:63], v[106:107]
	v_add_f32_dpp v108, v108, v108 quad_perm:[2,3,0,1] row_mask:0xf bank_mask:0xf bound_ctrl:1
	v_add_f32_dpp v102, v102, v102 row_half_mirror row_mask:0xf bank_mask:0xf bound_ctrl:1
	s_nop 0
	v_add_f32_dpp v108, v108, v108 row_half_mirror row_mask:0xf bank_mask:0xf bound_ctrl:1
	v_add_f32_dpp v102, v102, v102 row_mirror row_mask:0xf bank_mask:0xf bound_ctrl:1
	s_nop 0
	v_add_f32_dpp v108, v108, v108 row_mirror row_mask:0xf bank_mask:0xf bound_ctrl:1
	v_pk_fma_f32 v[52:53], v[64:65], v[102:103], v[104:105] op_sel_hi:[1,0,1] neg_lo:[0,1,0] neg_hi:[0,1,0]
	v_pk_fma_f32 v[54:55], v[66:67], v[102:103], v[106:107] op_sel_hi:[1,0,1] neg_lo:[0,1,0] neg_hi:[0,1,0]
	v_cndmask_b32_e64 v110, v110, v108, s[64:65]
	v_add_u32_e32 v111, s0, v132
	v_add_u32_e32 v132, s1, v132
	s_mov_b32 s3, s2
	s_cmpk_lt_u32 s2, 0x1fe
	s_waitcnt lgkmcnt(0)
	s_barrier
; #define LBAR() asm volatile("s_waitcnt lgkmcnt(0)\n\ts_barrier" ::: "memory")
; #define SC_STORE(R, B)                                                \
;   _Pragma("unroll") for (int i = 0; i < 6; ++i) *(f32x4*)(buf + (B) * SC_CH * SC_STEPF + pf[i]) = R[i];
; __device__ __forceinline__ void scan_unit(const Params p, int u, char* smem) {
;     ...
;   __syncthreads();
;   __builtin_amdgcn_s_setprio(3);
;   SC_LOAD(lregA, 0);
;   SC_STORE(lregA, 0);
;   SC_LOAD(lregB, 1);
;   __syncthreads();
;   for (int c = 0; c < nch; c += 2) {
;     SC_LOAD(lregA, c + 2);
;     SC_COMPUTE(c, 0);
;     SC_STORE(lregB, 1);
;     LBAR();
;     SC_LOAD(lregB, c + 3);
;     SC_COMPUTE(c + 1, 1);
;     SC_STORE(lregA, 0);
;     LBAR();
;   }
;   __builtin_amdgcn_s_setprio(0);
	s_cbranch_scc1 .LBB0_99
	v_pk_mul_f32 v[108:109], v[162:163], v[54:55]
	v_pk_fma_f32 v[108:109], v[160:161], v[52:53], v[108:109]
	v_add_f32_e32 v108, v108, v109
	s_nop 0
	s_nop 0
	v_add_f32_dpp v108, v108, v108 quad_perm:[1,0,3,2] row_mask:0xf bank_mask:0xf bound_ctrl:1
	s_nop 0
	s_nop 0
	v_add_f32_dpp v108, v108, v108 quad_perm:[2,3,0,1] row_mask:0xf bank_mask:0xf bound_ctrl:1
	s_nop 0
	s_nop 0
	v_add_f32_dpp v108, v108, v108 row_half_mirror row_mask:0xf bank_mask:0xf bound_ctrl:1
	s_nop 0
	s_nop 0
	v_add_f32_dpp v108, v108, v108 row_mirror row_mask:0xf bank_mask:0xf bound_ctrl:1
	v_cndmask_b32_e64 v110, v110, v108, s[66:67]
	global_store_dword v111, v110, s[96:97]
	s_waitcnt vmcnt(0)
	s_setprio 0
	v_readlane_b32 s52, v244, 4
	v_readlane_b32 s0, v245, 54
	v_readlane_b32 s56, v244, 8
	v_readlane_b32 s57, v244, 9
	v_readlane_b32 s58, v244, 10
	v_readlane_b32 s59, v244, 11
	v_readlane_b32 s60, v244, 12
	v_readlane_b32 s61, v244, 13
	v_readlane_b32 s62, v244, 14
	v_readlane_b32 s63, v244, 15
	v_readlane_b32 s64, v244, 16
	v_readlane_b32 s65, v244, 17
	s_add_i32 s70, s70, s86
	s_add_i32 s72, s72, s0
	v_readlane_b32 s66, v244, 18
	v_readlane_b32 s67, v244, 19
	v_readlane_b32 s56, v244, 21
	v_readlane_b32 s58, v244, 23
	v_readlane_b32 s60, v244, 25
	v_readlane_b32 s62, v244, 27
	v_readlane_b32 s64, v244, 29
	s_cmp_gt_i32 s70, 63
	v_readlane_b32 s53, v244, 5
	v_readlane_b32 s54, v244, 6
	v_readlane_b32 s55, v244, 7
	v_readlane_b32 s57, v244, 22
	v_readlane_b32 s59, v244, 24
	v_readlane_b32 s61, v244, 26
	v_readlane_b32 s63, v244, 28
	v_readlane_b32 s65, v244, 30
	v_readlane_b32 s66, v244, 31
	v_readlane_b32 s67, v244, 32
	v_readlane_b32 s50, v244, 33
	s_movk_i32 s51, 0x3ff
	v_readlane_b32 s48, v244, 34
	s_cbranch_scc0 .LBB0_62
	s_branch .LBB0_149

; template <int ATM>
; __device__ __forceinline__ void phase_attn_scan(const Params p, int l, char* smem) {
;     ...
;   if (ATM & 8) for (int u = lbid(); u < 64; u += gridDim.x) scan_unit(p, u, smem);
;   if ((ATM & 8) && (DUP_MASK & 2)) for (int u = lbid(); u < 64; u += gridDim.x) scan_unit(p, u, smem);
;   int* cnt = (int*)(ws + OFF_CNT) + l * 4;
;   const int* pos = (const int*)p.in[I_POS];
;   const int* kpmm = (const int*)(ws + OFF_KPMM);
;   const u16* P = (const u16*)(ws + OFF_P);
;   u16* OB = (u16*)(ws + OFF_OB);
;     ...
;   u16* OB2 = (u16*)(ws + OFF_OB2);
;   float* MLb = (float*)(ws + OFF_ML);
;   const int flip = (blockIdx.x >> 8) & 1;
;   for (int pass = 0; pass < 2; ++pass) {
.LBB0_149:
	s_lshr_b32 s0, s73, 6
	s_cmp_eq_u32 s0, 4
	s_cbranch_scc1 .LBB0_248
	v_readlane_b32 s0, v244, 43
	s_lshl_b32 s2, s0, 2
	v_readlane_b32 s1, v244, 44
	s_ashr_i32 s3, s2, 31
	s_lshl_b64 s[0:1], s[2:3], 2
	v_readlane_b32 s20, v247, 49
	v_readlane_b32 s21, v247, 50
	s_add_u32 s20, s20, s0
	s_addc_u32 s21, s21, s1
	s_mov_b32 s0, 0
	s_mov_b64 s[22:23], -1
	v_readlane_b32 s72, v244, 20
	s_branch .LBB0_151

; template <bool RWONLY>
; __device__ __forceinline__ void phase_prep(const Params p, int l, char* smem) {
;     ...
;           if (tid < 128) {
;             const float e2 = __builtin_amdgcn_exp2f(2.885390081777927f * v);
;             v = 1.f - 2.f * __builtin_amdgcn_rcpf(e2 + 1.f);
;           }
;           ld[tk * 256 + tid] = v;
;         }
;       }
;       __syncthreads();
;       float acc[8][4][2];
; #pragma unroll
;       for (int a = 0; a < 8; ++a)
; #pragma unroll
;         for (int b = 0; b < 4; ++b) acc[a][b][0] = acc[a][b][1] = 0.f;
;       for (int l4 = 0; l4 < 16; ++l4) {
;         float wv[4][4][2];
; #pragma unroll
;         for (int ll = 0; ll < 4; ++ll) {
; #pragma unroll
;           for (int ch = 0; ch < 2; ++ch) {
;             int c = tid + ch * 256;
;             int li = l4 * 4 + ll;
;             wv[0][ll][ch] = wup[(size_t)(0 * 64 + li) * 512 + c];
;             wv[1][ll][ch] = wup[(size_t)(1 * 64 + li) * 512 + c];
;             wv[2][ll][ch] = aup[(size_t)(0 * 64 + li) * 512 + c];
;             wv[3][ll][ch] = aup[(size_t)(1 * 64 + li) * 512 + c];
;           }
;         }
.LBB0_364:
	s_waitcnt vmcnt(0)
	v_pk_mul_f32 v[62:63], v[62:63], v[64:65]
	v_readlane_b32 s30, v244, 46
	v_fma_f32 v62, v68, v66, v62
	v_add_f32_e32 v62, v62, v63
	v_mul_f32_e32 v63, 0x4038aa3b, v62
	v_exp_f32_e32 v63, v63
	v_readlane_b32 s31, v244, 47
	s_ashr_i32 s57, s56, 31
	s_mul_hi_i32 s43, s56, 0x1c00
	v_add_f32_e32 v63, 1.0, v63
	v_rcp_f32_e32 v63, v63
	s_mul_i32 s42, s56, 0x1c00
	s_mul_hi_i32 s1, s20, 0x1c00
	s_mul_i32 s0, s20, 0x1c00
	v_fma_f32 v63, v63, -2.0, 1.0
	v_cndmask_b32_e64 v62, v62, v63, s[30:31]
	s_ashr_i32 s87, s86, 31
	s_mul_hi_i32 s45, s86, 0x1c00
	s_mul_i32 s44, s86, 0x1c00
	s_ashr_i32 s3, s2, 31
	s_mul_hi_i32 s47, s2, 0x1c00
	s_mul_i32 s46, s2, 0x1c00
	s_ashr_i32 s93, s92, 31
	s_mul_hi_i32 s49, s92, 0x1c00
	s_mul_i32 s48, s92, 0x1c00
	s_ashr_i32 s67, s66, 31
	s_mul_hi_i32 s51, s66, 0x1c00
	s_mul_i32 s50, s66, 0x1c00
	s_ashr_i32 s65, s64, 31
	s_mul_hi_i32 s53, s64, 0x1c00
	s_mul_i32 s52, s64, 0x1c00
	s_ashr_i32 s63, s62, 31
	s_mul_hi_i32 s55, s62, 0x1c00
	s_mul_i32 s54, s62, 0x1c00
	ds_write_b32 v161, v62 offset:7168
	s_mov_b64 s[90:91], 0
	s_mov_b32 s30, 0
	s_mov_b32 s31, 0
	v_mov_b32_e32 v95, v94
	v_mov_b32_e32 v98, v94
	v_mov_b32_e32 v99, v94
	v_mov_b32_e32 v96, v94
	v_mov_b32_e32 v97, v94
	v_mov_b32_e32 v100, v94
	v_mov_b32_e32 v101, v94
	v_mov_b32_e32 v104, v94
	v_mov_b32_e32 v105, v94
	v_mov_b32_e32 v106, v94
	v_mov_b32_e32 v107, v94
	v_mov_b32_e32 v102, v94
	v_mov_b32_e32 v103, v94
	v_mov_b32_e32 v108, v94
	v_mov_b32_e32 v109, v94
	v_mov_b32_e32 v112, v94
	v_mov_b32_e32 v113, v94
	v_mov_b32_e32 v114, v94
	v_mov_b32_e32 v115, v94
	v_mov_b32_e32 v110, v94
	v_mov_b32_e32 v111, v94
	v_mov_b32_e32 v116, v94
	v_mov_b32_e32 v117, v94
	v_mov_b32_e32 v118, v94
	v_mov_b32_e32 v119, v94
	v_mov_b32_e32 v122, v94
	v_mov_b32_e32 v123, v94
	v_mov_b32_e32 v120, v94
	v_mov_b32_e32 v121, v94
	v_mov_b32_e32 v124, v94
	v_mov_b32_e32 v125, v94
	v_mov_b32_e32 v90, v94
	v_mov_b32_e32 v91, v94
	v_mov_b32_e32 v86, v94
	v_mov_b32_e32 v87, v94
	v_mov_b32_e32 v92, v94
	v_mov_b32_e32 v93, v94
	v_mov_b32_e32 v88, v94
	v_mov_b32_e32 v89, v94
	v_mov_b32_e32 v82, v94
	v_mov_b32_e32 v83, v94
	v_mov_b32_e32 v78, v94
	v_mov_b32_e32 v79, v94
	v_mov_b32_e32 v84, v94
	v_mov_b32_e32 v85, v94
	v_mov_b32_e32 v80, v94
	v_mov_b32_e32 v81, v94
	v_mov_b32_e32 v74, v94
	v_mov_b32_e32 v75, v94
	v_mov_b32_e32 v70, v94
	v_mov_b32_e32 v71, v94
	v_mov_b32_e32 v76, v94
	v_mov_b32_e32 v77, v94
	v_mov_b32_e32 v72, v94
	v_mov_b32_e32 v73, v94
	v_mov_b32_e32 v66, v94
	v_mov_b32_e32 v67, v94
	v_mov_b32_e32 v62, v94
	v_mov_b32_e32 v63, v94
	v_mov_b32_e32 v68, v94
	v_mov_b32_e32 v69, v94
	v_mov_b32_e32 v64, v94
	v_mov_b32_e32 v65, v94
	s_waitcnt lgkmcnt(0)
	s_barrier
	v_mov_b32_e32 v174, v161
	v_add_u32_e32 v175, 0x1000, v161
	v_add_u32_e32 v158, 0x20000, v161
	v_add_u32_e32 v159, 0x21000, v161
	global_load_dword v126, v174, s[58:59]
	global_load_dword v127, v174, s[58:59] offset:1024
	global_load_dword v128, v174, s[58:59] offset:2048
	global_load_dword v129, v174, s[58:59] offset:3072
	global_load_dword v130, v175, s[58:59]
	global_load_dword v131, v175, s[58:59] offset:1024
	global_load_dword v132, v175, s[58:59] offset:2048
	global_load_dword v133, v175, s[58:59] offset:3072
	global_load_dword v134, v158, s[58:59]
	global_load_dword v135, v158, s[58:59] offset:1024
	global_load_dword v136, v158, s[58:59] offset:2048
	global_load_dword v137, v158, s[58:59] offset:3072
	global_load_dword v138, v159, s[58:59]
	global_load_dword v139, v159, s[58:59] offset:1024
	global_load_dword v140, v159, s[58:59] offset:2048
	global_load_dword v141, v159, s[58:59] offset:3072
	global_load_dword v142, v174, s[60:61]
	global_load_dword v143, v174, s[60:61] offset:1024
	global_load_dword v144, v174, s[60:61] offset:2048
	global_load_dword v145, v174, s[60:61] offset:3072
	global_load_dword v146, v175, s[60:61]
	global_load_dword v147, v175, s[60:61] offset:1024
	global_load_dword v148, v175, s[60:61] offset:2048
	global_load_dword v149, v175, s[60:61] offset:3072
	global_load_dword v150, v158, s[60:61]
	global_load_dword v151, v158, s[60:61] offset:1024
	global_load_dword v152, v158, s[60:61] offset:2048
	global_load_dword v153, v158, s[60:61] offset:3072
	global_load_dword v154, v159, s[60:61]
	global_load_dword v155, v159, s[60:61] offset:1024
	global_load_dword v156, v159, s[60:61] offset:2048
	global_load_dword v157, v159, s[60:61] offset:3072
; template <bool RWONLY>
; __device__ __forceinline__ void phase_prep(const Params p, int l, char* smem) {
;     ...
;       for (int l4 = 0; l4 < 16; ++l4) {
;         float wv[4][4][2];
; #pragma unroll
;         for (int ll = 0; ll < 4; ++ll) {
; #pragma unroll
;           for (int ch = 0; ch < 2; ++ch) {
;             int c = tid + ch * 256;
;             int li = l4 * 4 + ll;
;             wv[0][ll][ch] = wup[(size_t)(0 * 64 + li) * 512 + c];
;             wv[1][ll][ch] = wup[(size_t)(1 * 64 + li) * 512 + c];
;             wv[2][ll][ch] = aup[(size_t)(0 * 64 + li) * 512 + c];
;             wv[3][ll][ch] = aup[(size_t)(1 * 64 + li) * 512 + c];
;           }
;         }
; #pragma unroll
;         for (int tk = 0; tk < 8; ++tk) {
; #pragma unroll
;           for (int mat = 0; mat < 4; ++mat) {
;             float4 d = *(const float4*)(ld + tk * 256 + mat * 64 + l4 * 4);
; #pragma unroll
;             for (int ch = 0; ch < 2; ++ch) {
;               acc[tk][mat][ch] += d.x * wv[mat][0][ch] + d.y * wv[mat][1][ch] + d.z * wv[mat][2][ch] + d.w * wv[mat][3][ch];
;             }
;           }
;         }
.LBB0_365:
	v_add_u32_e32 v174, 0x2000, v174
	v_add_u32_e32 v175, 0x2000, v175
	v_add_u32_e32 v158, 0x2000, v158
	v_add_u32_e32 v159, 0x2000, v159
	global_load_dword v214, v174, s[58:59]
	global_load_dword v215, v174, s[58:59] offset:1024
	global_load_dword v216, v174, s[58:59] offset:2048
	global_load_dword v217, v174, s[58:59] offset:3072
	global_load_dword v218, v175, s[58:59]
	global_load_dword v219, v175, s[58:59] offset:1024
	global_load_dword v220, v175, s[58:59] offset:2048
	global_load_dword v221, v175, s[58:59] offset:3072
	global_load_dword v222, v158, s[58:59]
	global_load_dword v223, v158, s[58:59] offset:1024
	global_load_dword v224, v158, s[58:59] offset:2048
	global_load_dword v225, v158, s[58:59] offset:3072
	global_load_dword v226, v159, s[58:59]
	global_load_dword v227, v159, s[58:59] offset:1024
	global_load_dword v228, v159, s[58:59] offset:2048
	global_load_dword v229, v159, s[58:59] offset:3072
	global_load_dword v230, v174, s[60:61]
	global_load_dword v231, v174, s[60:61] offset:1024
	global_load_dword v232, v174, s[60:61] offset:2048
	global_load_dword v233, v174, s[60:61] offset:3072
	global_load_dword v234, v175, s[60:61]
	global_load_dword v235, v175, s[60:61] offset:1024
	global_load_dword v180, v175, s[60:61] offset:2048
	global_load_dword v181, v175, s[60:61] offset:3072
	global_load_dword v182, v158, s[60:61]
	global_load_dword v183, v158, s[60:61] offset:1024
	global_load_dword v184, v158, s[60:61] offset:2048
	global_load_dword v185, v158, s[60:61] offset:3072
	global_load_dword v186, v159, s[60:61]
	global_load_dword v187, v159, s[60:61] offset:1024
	global_load_dword v188, v159, s[60:61] offset:2048
	global_load_dword v189, v159, s[60:61] offset:3072
	v_mov_b32_e32 v172, s31
	s_add_i32 s31, s31, 16
	ds_read_b128 v[240:243], v172
	ds_read_b128 v[248:251], v172 offset:256
	ds_read_b128 v[252:255], v172 offset:512
	ds_read_b128 v[176:179], v172 offset:768
	s_waitcnt lgkmcnt(2)
	s_waitcnt vmcnt(32)
	v_pk_fma_f32 v[124:125], v[126:127], v[240:241], v[124:125] op_sel:[1,0,0] op_sel_hi:[0,0,1]
	v_pk_fma_f32 v[120:121], v[134:135], v[248:249], v[120:121] op_sel:[1,0,0] op_sel_hi:[0,0,1]
	v_pk_fma_f32 v[124:125], v[128:129], v[240:241], v[124:125] op_sel:[1,1,0] op_sel_hi:[0,1,1]
	v_pk_fma_f32 v[120:121], v[136:137], v[248:249], v[120:121] op_sel:[1,1,0] op_sel_hi:[0,1,1]
	v_pk_fma_f32 v[124:125], v[130:131], v[242:243], v[124:125] op_sel:[1,0,0] op_sel_hi:[0,0,1]
	v_pk_fma_f32 v[120:121], v[138:139], v[250:251], v[120:121] op_sel:[1,0,0] op_sel_hi:[0,0,1]
	v_pk_fma_f32 v[124:125], v[132:133], v[242:243], v[124:125] op_sel:[1,1,0] op_sel_hi:[0,1,1]
	v_pk_fma_f32 v[120:121], v[140:141], v[250:251], v[120:121] op_sel:[1,1,0] op_sel_hi:[0,1,1]
	ds_read_b128 v[240:243], v172 offset:1024
	ds_read_b128 v[248:251], v172 offset:1280
	s_waitcnt lgkmcnt(2)
	v_pk_fma_f32 v[122:123], v[142:143], v[252:253], v[122:123] op_sel:[1,0,0] op_sel_hi:[0,0,1]
	v_pk_fma_f32 v[118:119], v[150:151], v[176:177], v[118:119] op_sel:[1,0,0] op_sel_hi:[0,0,1]
	v_pk_fma_f32 v[122:123], v[144:145], v[252:253], v[122:123] op_sel:[1,1,0] op_sel_hi:[0,1,1]
	v_pk_fma_f32 v[118:119], v[152:153], v[176:177], v[118:119] op_sel:[1,1,0] op_sel_hi:[0,1,1]
	v_pk_fma_f32 v[122:123], v[146:147], v[254:255], v[122:123] op_sel:[1,0,0] op_sel_hi:[0,0,1]
	v_pk_fma_f32 v[118:119], v[154:155], v[178:179], v[118:119] op_sel:[1,0,0] op_sel_hi:[0,0,1]
	v_pk_fma_f32 v[122:123], v[148:149], v[254:255], v[122:123] op_sel:[1,1,0] op_sel_hi:[0,1,1]
	v_pk_fma_f32 v[118:119], v[156:157], v[178:179], v[118:119] op_sel:[1,1,0] op_sel_hi:[0,1,1]
	ds_read_b128 v[252:255], v172 offset:1536
	ds_read_b128 v[176:179], v172 offset:1792
	s_waitcnt lgkmcnt(2)
	v_pk_fma_f32 v[116:117], v[126:127], v[240:241], v[116:117] op_sel:[1,0,0] op_sel_hi:[0,0,1]
	v_pk_fma_f32 v[110:111], v[134:135], v[248:249], v[110:111] op_sel:[1,0,0] op_sel_hi:[0,0,1]
	v_pk_fma_f32 v[116:117], v[128:129], v[240:241], v[116:117] op_sel:[1,1,0] op_sel_hi:[0,1,1]
	v_pk_fma_f32 v[110:111], v[136:137], v[248:249], v[110:111] op_sel:[1,1,0] op_sel_hi:[0,1,1]
	v_pk_fma_f32 v[116:117], v[130:131], v[242:243], v[116:117] op_sel:[1,0,0] op_sel_hi:[0,0,1]
	v_pk_fma_f32 v[110:111], v[138:139], v[250:251], v[110:111] op_sel:[1,0,0] op_sel_hi:[0,0,1]
	v_pk_fma_f32 v[116:117], v[132:133], v[242:243], v[116:117] op_sel:[1,1,0] op_sel_hi:[0,1,1]
	v_pk_fma_f32 v[110:111], v[140:141], v[250:251], v[110:111] op_sel:[1,1,0] op_sel_hi:[0,1,1]
	ds_read_b128 v[240:243], v172 offset:2048
	ds_read_b128 v[248:251], v172 offset:2304
	s_waitcnt lgkmcnt(2)
	v_pk_fma_f32 v[114:115], v[142:143], v[252:253], v[114:115] op_sel:[1,0,0] op_sel_hi:[0,0,1]
	v_pk_fma_f32 v[112:113], v[150:151], v[176:177], v[112:113] op_sel:[1,0,0] op_sel_hi:[0,0,1]
	v_pk_fma_f32 v[114:115], v[144:145], v[252:253], v[114:115] op_sel:[1,1,0] op_sel_hi:[0,1,1]
	v_pk_fma_f32 v[112:113], v[152:153], v[176:177], v[112:113] op_sel:[1,1,0] op_sel_hi:[0,1,1]
	v_pk_fma_f32 v[114:115], v[146:147], v[254:255], v[114:115] op_sel:[1,0,0] op_sel_hi:[0,0,1]
	v_pk_fma_f32 v[112:113], v[154:155], v[178:179], v[112:113] op_sel:[1,0,0] op_sel_hi:[0,0,1]
	v_pk_fma_f32 v[114:115], v[148:149], v[254:255], v[114:115] op_sel:[1,1,0] op_sel_hi:[0,1,1]
	v_pk_fma_f32 v[112:113], v[156:157], v[178:179], v[112:113] op_sel:[1,1,0] op_sel_hi:[0,1,1]
	ds_read_b128 v[252:255], v172 offset:2560
	ds_read_b128 v[176:179], v172 offset:2816
	s_waitcnt lgkmcnt(2)
; template <bool RWONLY>
; __device__ __forceinline__ void phase_prep(const Params p, int l, char* smem) {
;     ...
; #pragma unroll
;         for (int tk = 0; tk < 8; ++tk) {
; #pragma unroll
;           for (int mat = 0; mat < 4; ++mat) {
;             float4 d = *(const float4*)(ld + tk * 256 + mat * 64 + l4 * 4);
; #pragma unroll
;             for (int ch = 0; ch < 2; ++ch) {
;               acc[tk][mat][ch] += d.x * wv[mat][0][ch] + d.y * wv[mat][1][ch] + d.z * wv[mat][2][ch] + d.w * wv[mat][3][ch];
;             }
;           }
;         }
	v_pk_fma_f32 v[108:109], v[126:127], v[240:241], v[108:109] op_sel:[1,0,0] op_sel_hi:[0,0,1]
	v_pk_fma_f32 v[102:103], v[134:135], v[248:249], v[102:103] op_sel:[1,0,0] op_sel_hi:[0,0,1]
	v_pk_fma_f32 v[108:109], v[128:129], v[240:241], v[108:109] op_sel:[1,1,0] op_sel_hi:[0,1,1]
	v_pk_fma_f32 v[102:103], v[136:137], v[248:249], v[102:103] op_sel:[1,1,0] op_sel_hi:[0,1,1]
	v_pk_fma_f32 v[108:109], v[130:131], v[242:243], v[108:109] op_sel:[1,0,0] op_sel_hi:[0,0,1]
	v_pk_fma_f32 v[102:103], v[138:139], v[250:251], v[102:103] op_sel:[1,0,0] op_sel_hi:[0,0,1]
	v_pk_fma_f32 v[108:109], v[132:133], v[242:243], v[108:109] op_sel:[1,1,0] op_sel_hi:[0,1,1]
	v_pk_fma_f32 v[102:103], v[140:141], v[250:251], v[102:103] op_sel:[1,1,0] op_sel_hi:[0,1,1]
	ds_read_b128 v[240:243], v172 offset:3072
	ds_read_b128 v[248:251], v172 offset:3328
	s_waitcnt lgkmcnt(2)
	v_pk_fma_f32 v[106:107], v[142:143], v[252:253], v[106:107] op_sel:[1,0,0] op_sel_hi:[0,0,1]
	v_pk_fma_f32 v[104:105], v[150:151], v[176:177], v[104:105] op_sel:[1,0,0] op_sel_hi:[0,0,1]
	v_pk_fma_f32 v[106:107], v[144:145], v[252:253], v[106:107] op_sel:[1,1,0] op_sel_hi:[0,1,1]
	v_pk_fma_f32 v[104:105], v[152:153], v[176:177], v[104:105] op_sel:[1,1,0] op_sel_hi:[0,1,1]
	v_pk_fma_f32 v[106:107], v[146:147], v[254:255], v[106:107] op_sel:[1,0,0] op_sel_hi:[0,0,1]
	v_pk_fma_f32 v[104:105], v[154:155], v[178:179], v[104:105] op_sel:[1,0,0] op_sel_hi:[0,0,1]
	v_pk_fma_f32 v[106:107], v[148:149], v[254:255], v[106:107] op_sel:[1,1,0] op_sel_hi:[0,1,1]
	v_pk_fma_f32 v[104:105], v[156:157], v[178:179], v[104:105] op_sel:[1,1,0] op_sel_hi:[0,1,1]
	ds_read_b128 v[252:255], v172 offset:3584
	ds_read_b128 v[176:179], v172 offset:3840
	s_waitcnt lgkmcnt(2)
	v_pk_fma_f32 v[100:101], v[126:127], v[240:241], v[100:101] op_sel:[1,0,0] op_sel_hi:[0,0,1]
	v_pk_fma_f32 v[96:97], v[134:135], v[248:249], v[96:97] op_sel:[1,0,0] op_sel_hi:[0,0,1]
	v_pk_fma_f32 v[100:101], v[128:129], v[240:241], v[100:101] op_sel:[1,1,0] op_sel_hi:[0,1,1]
	v_pk_fma_f32 v[96:97], v[136:137], v[248:249], v[96:97] op_sel:[1,1,0] op_sel_hi:[0,1,1]
	v_pk_fma_f32 v[100:101], v[130:131], v[242:243], v[100:101] op_sel:[1,0,0] op_sel_hi:[0,0,1]
	v_pk_fma_f32 v[96:97], v[138:139], v[250:251], v[96:97] op_sel:[1,0,0] op_sel_hi:[0,0,1]
	v_pk_fma_f32 v[100:101], v[132:133], v[242:243], v[100:101] op_sel:[1,1,0] op_sel_hi:[0,1,1]
	v_pk_fma_f32 v[96:97], v[140:141], v[250:251], v[96:97] op_sel:[1,1,0] op_sel_hi:[0,1,1]
	ds_read_b128 v[240:243], v172 offset:4096
	ds_read_b128 v[248:251], v172 offset:4352
	s_waitcnt lgkmcnt(2)
	v_pk_fma_f32 v[98:99], v[142:143], v[252:253], v[98:99] op_sel:[1,0,0] op_sel_hi:[0,0,1]
	v_pk_fma_f32 v[94:95], v[150:151], v[176:177], v[94:95] op_sel:[1,0,0] op_sel_hi:[0,0,1]
	v_pk_fma_f32 v[98:99], v[144:145], v[252:253], v[98:99] op_sel:[1,1,0] op_sel_hi:[0,1,1]
	v_pk_fma_f32 v[94:95], v[152:153], v[176:177], v[94:95] op_sel:[1,1,0] op_sel_hi:[0,1,1]
	v_pk_fma_f32 v[98:99], v[146:147], v[254:255], v[98:99] op_sel:[1,0,0] op_sel_hi:[0,0,1]
	v_pk_fma_f32 v[94:95], v[154:155], v[178:179], v[94:95] op_sel:[1,0,0] op_sel_hi:[0,0,1]
	v_pk_fma_f32 v[98:99], v[148:149], v[254:255], v[98:99] op_sel:[1,1,0] op_sel_hi:[0,1,1]
	v_pk_fma_f32 v[94:95], v[156:157], v[178:179], v[94:95] op_sel:[1,1,0] op_sel_hi:[0,1,1]
	ds_read_b128 v[252:255], v172 offset:4608
	ds_read_b128 v[176:179], v172 offset:4864
	s_waitcnt lgkmcnt(2)
	v_pk_fma_f32 v[90:91], v[126:127], v[240:241], v[90:91] op_sel:[0,0,0] op_sel_hi:[1,0,1]
	v_pk_fma_f32 v[86:87], v[134:135], v[248:249], v[86:87] op_sel:[0,0,0] op_sel_hi:[1,0,1]
	v_pk_fma_f32 v[90:91], v[128:129], v[240:241], v[90:91] op_sel:[0,1,0] op_sel_hi:[1,1,1]
	v_pk_fma_f32 v[86:87], v[136:137], v[248:249], v[86:87] op_sel:[0,1,0] op_sel_hi:[1,1,1]
	v_pk_fma_f32 v[90:91], v[130:131], v[242:243], v[90:91] op_sel:[0,0,0] op_sel_hi:[1,0,1]
	v_pk_fma_f32 v[86:87], v[138:139], v[250:251], v[86:87] op_sel:[0,0,0] op_sel_hi:[1,0,1]
	v_pk_fma_f32 v[90:91], v[132:133], v[242:243], v[90:91] op_sel:[0,1,0] op_sel_hi:[1,1,1]
	v_pk_fma_f32 v[86:87], v[140:141], v[250:251], v[86:87] op_sel:[0,1,0] op_sel_hi:[1,1,1]
	ds_read_b128 v[240:243], v172 offset:5120
	ds_read_b128 v[248:251], v172 offset:5376
	s_waitcnt lgkmcnt(2)
	v_pk_fma_f32 v[92:93], v[142:143], v[252:253], v[92:93] op_sel:[0,0,0] op_sel_hi:[1,0,1]
	v_pk_fma_f32 v[88:89], v[150:151], v[176:177], v[88:89] op_sel:[0,0,0] op_sel_hi:[1,0,1]
	v_pk_fma_f32 v[92:93], v[144:145], v[252:253], v[92:93] op_sel:[0,1,0] op_sel_hi:[1,1,1]
	v_pk_fma_f32 v[88:89], v[152:153], v[176:177], v[88:89] op_sel:[0,1,0] op_sel_hi:[1,1,1]
	v_pk_fma_f32 v[92:93], v[146:147], v[254:255], v[92:93] op_sel:[0,0,0] op_sel_hi:[1,0,1]
	v_pk_fma_f32 v[88:89], v[154:155], v[178:179], v[88:89] op_sel:[0,0,0] op_sel_hi:[1,0,1]
	v_pk_fma_f32 v[92:93], v[148:149], v[254:255], v[92:93] op_sel:[0,1,0] op_sel_hi:[1,1,1]
	v_pk_fma_f32 v[88:89], v[156:157], v[178:179], v[88:89] op_sel:[0,1,0] op_sel_hi:[1,1,1]
	ds_read_b128 v[252:255], v172 offset:5632
	ds_read_b128 v[176:179], v172 offset:5888
	s_waitcnt lgkmcnt(2)
	v_pk_fma_f32 v[82:83], v[126:127], v[240:241], v[82:83] op_sel:[0,0,0] op_sel_hi:[1,0,1]
	v_pk_fma_f32 v[78:79], v[134:135], v[248:249], v[78:79] op_sel:[0,0,0] op_sel_hi:[1,0,1]
	v_pk_fma_f32 v[82:83], v[128:129], v[240:241], v[82:83] op_sel:[0,1,0] op_sel_hi:[1,1,1]
	v_pk_fma_f32 v[78:79], v[136:137], v[248:249], v[78:79] op_sel:[0,1,0] op_sel_hi:[1,1,1]
	v_pk_fma_f32 v[82:83], v[130:131], v[242:243], v[82:83] op_sel:[0,0,0] op_sel_hi:[1,0,1]
	v_pk_fma_f32 v[78:79], v[138:139], v[250:251], v[78:79] op_sel:[0,0,0] op_sel_hi:[1,0,1]
	v_pk_fma_f32 v[82:83], v[132:133], v[242:243], v[82:83] op_sel:[0,1,0] op_sel_hi:[1,1,1]
	v_pk_fma_f32 v[78:79], v[140:141], v[250:251], v[78:79] op_sel:[0,1,0] op_sel_hi:[1,1,1]
	ds_read_b128 v[240:243], v172 offset:6144
	ds_read_b128 v[248:251], v172 offset:6400
	s_waitcnt lgkmcnt(2)
; template <bool RWONLY>
; __device__ __forceinline__ void phase_prep(const Params p, int l, char* smem) {
;     ...
;       for (int l4 = 0; l4 < 16; ++l4) {
;         float wv[4][4][2];
; #pragma unroll
;         for (int ll = 0; ll < 4; ++ll) {
; #pragma unroll
;           for (int ch = 0; ch < 2; ++ch) {
;             int c = tid + ch * 256;
;             int li = l4 * 4 + ll;
;             wv[0][ll][ch] = wup[(size_t)(0 * 64 + li) * 512 + c];
;             wv[1][ll][ch] = wup[(size_t)(1 * 64 + li) * 512 + c];
;             wv[2][ll][ch] = aup[(size_t)(0 * 64 + li) * 512 + c];
;             wv[3][ll][ch] = aup[(size_t)(1 * 64 + li) * 512 + c];
;           }
;         }
; #pragma unroll
;         for (int tk = 0; tk < 8; ++tk) {
; #pragma unroll
;           for (int mat = 0; mat < 4; ++mat) {
;             float4 d = *(const float4*)(ld + tk * 256 + mat * 64 + l4 * 4);
; #pragma unroll
;             for (int ch = 0; ch < 2; ++ch) {
;               acc[tk][mat][ch] += d.x * wv[mat][0][ch] + d.y * wv[mat][1][ch] + d.z * wv[mat][2][ch] + d.w * wv[mat][3][ch];
;             }
;           }
;         }
	v_pk_fma_f32 v[84:85], v[142:143], v[252:253], v[84:85] op_sel:[0,0,0] op_sel_hi:[1,0,1]
	v_pk_fma_f32 v[80:81], v[150:151], v[176:177], v[80:81] op_sel:[0,0,0] op_sel_hi:[1,0,1]
	v_pk_fma_f32 v[84:85], v[144:145], v[252:253], v[84:85] op_sel:[0,1,0] op_sel_hi:[1,1,1]
	v_pk_fma_f32 v[80:81], v[152:153], v[176:177], v[80:81] op_sel:[0,1,0] op_sel_hi:[1,1,1]
	v_pk_fma_f32 v[84:85], v[146:147], v[254:255], v[84:85] op_sel:[0,0,0] op_sel_hi:[1,0,1]
	v_pk_fma_f32 v[80:81], v[154:155], v[178:179], v[80:81] op_sel:[0,0,0] op_sel_hi:[1,0,1]
	v_pk_fma_f32 v[84:85], v[148:149], v[254:255], v[84:85] op_sel:[0,1,0] op_sel_hi:[1,1,1]
	v_pk_fma_f32 v[80:81], v[156:157], v[178:179], v[80:81] op_sel:[0,1,0] op_sel_hi:[1,1,1]
	ds_read_b128 v[252:255], v172 offset:6656
	ds_read_b128 v[176:179], v172 offset:6912
	s_waitcnt lgkmcnt(2)
	v_pk_fma_f32 v[74:75], v[126:127], v[240:241], v[74:75] op_sel:[0,0,0] op_sel_hi:[1,0,1]
	v_pk_fma_f32 v[70:71], v[134:135], v[248:249], v[70:71] op_sel:[0,0,0] op_sel_hi:[1,0,1]
	v_pk_fma_f32 v[74:75], v[128:129], v[240:241], v[74:75] op_sel:[0,1,0] op_sel_hi:[1,1,1]
	v_pk_fma_f32 v[70:71], v[136:137], v[248:249], v[70:71] op_sel:[0,1,0] op_sel_hi:[1,1,1]
	v_pk_fma_f32 v[74:75], v[130:131], v[242:243], v[74:75] op_sel:[0,0,0] op_sel_hi:[1,0,1]
	v_pk_fma_f32 v[70:71], v[138:139], v[250:251], v[70:71] op_sel:[0,0,0] op_sel_hi:[1,0,1]
	v_pk_fma_f32 v[74:75], v[132:133], v[242:243], v[74:75] op_sel:[0,1,0] op_sel_hi:[1,1,1]
	v_pk_fma_f32 v[70:71], v[140:141], v[250:251], v[70:71] op_sel:[0,1,0] op_sel_hi:[1,1,1]
	ds_read_b128 v[240:243], v172 offset:7168
	ds_read_b128 v[248:251], v172 offset:7424
	s_waitcnt lgkmcnt(2)
	v_pk_fma_f32 v[76:77], v[142:143], v[252:253], v[76:77] op_sel:[0,0,0] op_sel_hi:[1,0,1]
	v_pk_fma_f32 v[72:73], v[150:151], v[176:177], v[72:73] op_sel:[0,0,0] op_sel_hi:[1,0,1]
	v_pk_fma_f32 v[76:77], v[144:145], v[252:253], v[76:77] op_sel:[0,1,0] op_sel_hi:[1,1,1]
	v_pk_fma_f32 v[72:73], v[152:153], v[176:177], v[72:73] op_sel:[0,1,0] op_sel_hi:[1,1,1]
	v_pk_fma_f32 v[76:77], v[146:147], v[254:255], v[76:77] op_sel:[0,0,0] op_sel_hi:[1,0,1]
	v_pk_fma_f32 v[72:73], v[154:155], v[178:179], v[72:73] op_sel:[0,0,0] op_sel_hi:[1,0,1]
	v_pk_fma_f32 v[76:77], v[148:149], v[254:255], v[76:77] op_sel:[0,1,0] op_sel_hi:[1,1,1]
	v_pk_fma_f32 v[72:73], v[156:157], v[178:179], v[72:73] op_sel:[0,1,0] op_sel_hi:[1,1,1]
	ds_read_b128 v[252:255], v172 offset:7680
	ds_read_b128 v[176:179], v172 offset:7936
	s_waitcnt lgkmcnt(2)
	v_pk_fma_f32 v[66:67], v[126:127], v[240:241], v[66:67] op_sel:[0,0,0] op_sel_hi:[1,0,1]
	v_pk_fma_f32 v[62:63], v[134:135], v[248:249], v[62:63] op_sel:[0,0,0] op_sel_hi:[1,0,1]
	v_pk_fma_f32 v[66:67], v[128:129], v[240:241], v[66:67] op_sel:[0,1,0] op_sel_hi:[1,1,1]
	v_pk_fma_f32 v[62:63], v[136:137], v[248:249], v[62:63] op_sel:[0,1,0] op_sel_hi:[1,1,1]
	v_pk_fma_f32 v[66:67], v[130:131], v[242:243], v[66:67] op_sel:[0,0,0] op_sel_hi:[1,0,1]
	v_pk_fma_f32 v[62:63], v[138:139], v[250:251], v[62:63] op_sel:[0,0,0] op_sel_hi:[1,0,1]
	v_pk_fma_f32 v[66:67], v[132:133], v[242:243], v[66:67] op_sel:[0,1,0] op_sel_hi:[1,1,1]
	v_pk_fma_f32 v[62:63], v[140:141], v[250:251], v[62:63] op_sel:[0,1,0] op_sel_hi:[1,1,1]
	s_waitcnt lgkmcnt(0)
	v_pk_fma_f32 v[68:69], v[142:143], v[252:253], v[68:69] op_sel:[0,0,0] op_sel_hi:[1,0,1]
	v_pk_fma_f32 v[64:65], v[150:151], v[176:177], v[64:65] op_sel:[0,0,0] op_sel_hi:[1,0,1]
	v_pk_fma_f32 v[68:69], v[144:145], v[252:253], v[68:69] op_sel:[0,1,0] op_sel_hi:[1,1,1]
	v_pk_fma_f32 v[64:65], v[152:153], v[176:177], v[64:65] op_sel:[0,1,0] op_sel_hi:[1,1,1]
	v_pk_fma_f32 v[68:69], v[146:147], v[254:255], v[68:69] op_sel:[0,0,0] op_sel_hi:[1,0,1]
	v_pk_fma_f32 v[64:65], v[154:155], v[178:179], v[64:65] op_sel:[0,0,0] op_sel_hi:[1,0,1]
	v_pk_fma_f32 v[68:69], v[148:149], v[254:255], v[68:69] op_sel:[0,1,0] op_sel_hi:[1,1,1]
	v_pk_fma_f32 v[64:65], v[156:157], v[178:179], v[64:65] op_sel:[0,1,0] op_sel_hi:[1,1,1]
	s_add_u32 s90, s90, 0x4000
	s_cmp_eq_u32 s90, 0x20000
	s_cbranch_scc1 .Lprep_l4_last
	v_add_u32_e32 v174, 0x2000, v174
	v_add_u32_e32 v175, 0x2000, v175
	v_add_u32_e32 v158, 0x2000, v158
	v_add_u32_e32 v159, 0x2000, v159
	global_load_dword v126, v174, s[58:59]
	global_load_dword v127, v174, s[58:59] offset:1024
	global_load_dword v128, v174, s[58:59] offset:2048
	global_load_dword v129, v174, s[58:59] offset:3072
	global_load_dword v130, v175, s[58:59]
	global_load_dword v131, v175, s[58:59] offset:1024
	global_load_dword v132, v175, s[58:59] offset:2048
	global_load_dword v133, v175, s[58:59] offset:3072
	global_load_dword v134, v158, s[58:59]
	global_load_dword v135, v158, s[58:59] offset:1024
	global_load_dword v136, v158, s[58:59] offset:2048
	global_load_dword v137, v158, s[58:59] offset:3072
	global_load_dword v138, v159, s[58:59]
	global_load_dword v139, v159, s[58:59] offset:1024
	global_load_dword v140, v159, s[58:59] offset:2048
	global_load_dword v141, v159, s[58:59] offset:3072
	global_load_dword v142, v174, s[60:61]
	global_load_dword v143, v174, s[60:61] offset:1024
	global_load_dword v144, v174, s[60:61] offset:2048
	global_load_dword v145, v174, s[60:61] offset:3072
	global_load_dword v146, v175, s[60:61]
	global_load_dword v147, v175, s[60:61] offset:1024
	global_load_dword v148, v175, s[60:61] offset:2048
	global_load_dword v149, v175, s[60:61] offset:3072
	global_load_dword v150, v158, s[60:61]
	global_load_dword v151, v158, s[60:61] offset:1024
	global_load_dword v152, v158, s[60:61] offset:2048
	global_load_dword v153, v158, s[60:61] offset:3072
	global_load_dword v154, v159, s[60:61]
	global_load_dword v155, v159, s[60:61] offset:1024
	global_load_dword v156, v159, s[60:61] offset:2048
	global_load_dword v157, v159, s[60:61] offset:3072
	s_branch .Lprep_l4_join

; template <bool RWONLY>
; __device__ __forceinline__ void phase_prep(const Params p, int l, char* smem) {
;     ...
; #pragma unroll
;         for (int tk = 0; tk < 8; ++tk) {
; #pragma unroll
;           for (int mat = 0; mat < 4; ++mat) {
;             float4 d = *(const float4*)(ld + tk * 256 + mat * 64 + l4 * 4);
; #pragma unroll
;             for (int ch = 0; ch < 2; ++ch) {
;               acc[tk][mat][ch] += d.x * wv[mat][0][ch] + d.y * wv[mat][1][ch] + d.z * wv[mat][2][ch] + d.w * wv[mat][3][ch];
;             }
;           }
;         }
.Lprep_l4_join:
	v_mov_b32_e32 v172, s31
	s_add_i32 s31, s31, 16
	ds_read_b128 v[240:243], v172
	ds_read_b128 v[248:251], v172 offset:256
	ds_read_b128 v[252:255], v172 offset:512
	ds_read_b128 v[176:179], v172 offset:768
	s_waitcnt lgkmcnt(2)
	s_waitcnt vmcnt(32)
	v_pk_fma_f32 v[124:125], v[214:215], v[240:241], v[124:125] op_sel:[1,0,0] op_sel_hi:[0,0,1]
	v_pk_fma_f32 v[120:121], v[222:223], v[248:249], v[120:121] op_sel:[1,0,0] op_sel_hi:[0,0,1]
	v_pk_fma_f32 v[124:125], v[216:217], v[240:241], v[124:125] op_sel:[1,1,0] op_sel_hi:[0,1,1]
	v_pk_fma_f32 v[120:121], v[224:225], v[248:249], v[120:121] op_sel:[1,1,0] op_sel_hi:[0,1,1]
	v_pk_fma_f32 v[124:125], v[218:219], v[242:243], v[124:125] op_sel:[1,0,0] op_sel_hi:[0,0,1]
	v_pk_fma_f32 v[120:121], v[226:227], v[250:251], v[120:121] op_sel:[1,0,0] op_sel_hi:[0,0,1]
	v_pk_fma_f32 v[124:125], v[220:221], v[242:243], v[124:125] op_sel:[1,1,0] op_sel_hi:[0,1,1]
	v_pk_fma_f32 v[120:121], v[228:229], v[250:251], v[120:121] op_sel:[1,1,0] op_sel_hi:[0,1,1]
	ds_read_b128 v[240:243], v172 offset:1024
	ds_read_b128 v[248:251], v172 offset:1280
	s_waitcnt lgkmcnt(2)
	v_pk_fma_f32 v[122:123], v[230:231], v[252:253], v[122:123] op_sel:[1,0,0] op_sel_hi:[0,0,1]
	v_pk_fma_f32 v[118:119], v[182:183], v[176:177], v[118:119] op_sel:[1,0,0] op_sel_hi:[0,0,1]
	v_pk_fma_f32 v[122:123], v[232:233], v[252:253], v[122:123] op_sel:[1,1,0] op_sel_hi:[0,1,1]
	v_pk_fma_f32 v[118:119], v[184:185], v[176:177], v[118:119] op_sel:[1,1,0] op_sel_hi:[0,1,1]
	v_pk_fma_f32 v[122:123], v[234:235], v[254:255], v[122:123] op_sel:[1,0,0] op_sel_hi:[0,0,1]
	v_pk_fma_f32 v[118:119], v[186:187], v[178:179], v[118:119] op_sel:[1,0,0] op_sel_hi:[0,0,1]
	v_pk_fma_f32 v[122:123], v[180:181], v[254:255], v[122:123] op_sel:[1,1,0] op_sel_hi:[0,1,1]
	v_pk_fma_f32 v[118:119], v[188:189], v[178:179], v[118:119] op_sel:[1,1,0] op_sel_hi:[0,1,1]
	ds_read_b128 v[252:255], v172 offset:1536
	ds_read_b128 v[176:179], v172 offset:1792
	s_waitcnt lgkmcnt(2)
	v_pk_fma_f32 v[116:117], v[214:215], v[240:241], v[116:117] op_sel:[1,0,0] op_sel_hi:[0,0,1]
	v_pk_fma_f32 v[110:111], v[222:223], v[248:249], v[110:111] op_sel:[1,0,0] op_sel_hi:[0,0,1]
	v_pk_fma_f32 v[116:117], v[216:217], v[240:241], v[116:117] op_sel:[1,1,0] op_sel_hi:[0,1,1]
	v_pk_fma_f32 v[110:111], v[224:225], v[248:249], v[110:111] op_sel:[1,1,0] op_sel_hi:[0,1,1]
	v_pk_fma_f32 v[116:117], v[218:219], v[242:243], v[116:117] op_sel:[1,0,0] op_sel_hi:[0,0,1]
	v_pk_fma_f32 v[110:111], v[226:227], v[250:251], v[110:111] op_sel:[1,0,0] op_sel_hi:[0,0,1]
	v_pk_fma_f32 v[116:117], v[220:221], v[242:243], v[116:117] op_sel:[1,1,0] op_sel_hi:[0,1,1]
	v_pk_fma_f32 v[110:111], v[228:229], v[250:251], v[110:111] op_sel:[1,1,0] op_sel_hi:[0,1,1]
	ds_read_b128 v[240:243], v172 offset:2048
	ds_read_b128 v[248:251], v172 offset:2304
	s_waitcnt lgkmcnt(2)
	v_pk_fma_f32 v[114:115], v[230:231], v[252:253], v[114:115] op_sel:[1,0,0] op_sel_hi:[0,0,1]
	v_pk_fma_f32 v[112:113], v[182:183], v[176:177], v[112:113] op_sel:[1,0,0] op_sel_hi:[0,0,1]
	v_pk_fma_f32 v[114:115], v[232:233], v[252:253], v[114:115] op_sel:[1,1,0] op_sel_hi:[0,1,1]
	v_pk_fma_f32 v[112:113], v[184:185], v[176:177], v[112:113] op_sel:[1,1,0] op_sel_hi:[0,1,1]
	v_pk_fma_f32 v[114:115], v[234:235], v[254:255], v[114:115] op_sel:[1,0,0] op_sel_hi:[0,0,1]
	v_pk_fma_f32 v[112:113], v[186:187], v[178:179], v[112:113] op_sel:[1,0,0] op_sel_hi:[0,0,1]
	v_pk_fma_f32 v[114:115], v[180:181], v[254:255], v[114:115] op_sel:[1,1,0] op_sel_hi:[0,1,1]
	v_pk_fma_f32 v[112:113], v[188:189], v[178:179], v[112:113] op_sel:[1,1,0] op_sel_hi:[0,1,1]
	ds_read_b128 v[252:255], v172 offset:2560
	ds_read_b128 v[176:179], v172 offset:2816
	s_waitcnt lgkmcnt(2)
	v_pk_fma_f32 v[108:109], v[214:215], v[240:241], v[108:109] op_sel:[1,0,0] op_sel_hi:[0,0,1]
	v_pk_fma_f32 v[102:103], v[222:223], v[248:249], v[102:103] op_sel:[1,0,0] op_sel_hi:[0,0,1]
	v_pk_fma_f32 v[108:109], v[216:217], v[240:241], v[108:109] op_sel:[1,1,0] op_sel_hi:[0,1,1]
	v_pk_fma_f32 v[102:103], v[224:225], v[248:249], v[102:103] op_sel:[1,1,0] op_sel_hi:[0,1,1]
	v_pk_fma_f32 v[108:109], v[218:219], v[242:243], v[108:109] op_sel:[1,0,0] op_sel_hi:[0,0,1]
	v_pk_fma_f32 v[102:103], v[226:227], v[250:251], v[102:103] op_sel:[1,0,0] op_sel_hi:[0,0,1]
	v_pk_fma_f32 v[108:109], v[220:221], v[242:243], v[108:109] op_sel:[1,1,0] op_sel_hi:[0,1,1]
	v_pk_fma_f32 v[102:103], v[228:229], v[250:251], v[102:103] op_sel:[1,1,0] op_sel_hi:[0,1,1]
	ds_read_b128 v[240:243], v172 offset:3072
	ds_read_b128 v[248:251], v172 offset:3328
	s_waitcnt lgkmcnt(2)
	v_pk_fma_f32 v[106:107], v[230:231], v[252:253], v[106:107] op_sel:[1,0,0] op_sel_hi:[0,0,1]
	v_pk_fma_f32 v[104:105], v[182:183], v[176:177], v[104:105] op_sel:[1,0,0] op_sel_hi:[0,0,1]
	v_pk_fma_f32 v[106:107], v[232:233], v[252:253], v[106:107] op_sel:[1,1,0] op_sel_hi:[0,1,1]
	v_pk_fma_f32 v[104:105], v[184:185], v[176:177], v[104:105] op_sel:[1,1,0] op_sel_hi:[0,1,1]
	v_pk_fma_f32 v[106:107], v[234:235], v[254:255], v[106:107] op_sel:[1,0,0] op_sel_hi:[0,0,1]
	v_pk_fma_f32 v[104:105], v[186:187], v[178:179], v[104:105] op_sel:[1,0,0] op_sel_hi:[0,0,1]
	v_pk_fma_f32 v[106:107], v[180:181], v[254:255], v[106:107] op_sel:[1,1,0] op_sel_hi:[0,1,1]
	v_pk_fma_f32 v[104:105], v[188:189], v[178:179], v[104:105] op_sel:[1,1,0] op_sel_hi:[0,1,1]
	ds_read_b128 v[252:255], v172 offset:3584
	ds_read_b128 v[176:179], v172 offset:3840
	s_waitcnt lgkmcnt(2)
; template <bool RWONLY>
; __device__ __forceinline__ void phase_prep(const Params p, int l, char* smem) {
;     ...
;       for (int l4 = 0; l4 < 16; ++l4) {
;         float wv[4][4][2];
; #pragma unroll
;         for (int ll = 0; ll < 4; ++ll) {
; #pragma unroll
;           for (int ch = 0; ch < 2; ++ch) {
;             int c = tid + ch * 256;
;             int li = l4 * 4 + ll;
;             wv[0][ll][ch] = wup[(size_t)(0 * 64 + li) * 512 + c];
;             wv[1][ll][ch] = wup[(size_t)(1 * 64 + li) * 512 + c];
;             wv[2][ll][ch] = aup[(size_t)(0 * 64 + li) * 512 + c];
;             wv[3][ll][ch] = aup[(size_t)(1 * 64 + li) * 512 + c];
;           }
;         }
; #pragma unroll
;         for (int tk = 0; tk < 8; ++tk) {
; #pragma unroll
;           for (int mat = 0; mat < 4; ++mat) {
;             float4 d = *(const float4*)(ld + tk * 256 + mat * 64 + l4 * 4);
; #pragma unroll
;             for (int ch = 0; ch < 2; ++ch) {
;               acc[tk][mat][ch] += d.x * wv[mat][0][ch] + d.y * wv[mat][1][ch] + d.z * wv[mat][2][ch] + d.w * wv[mat][3][ch];
;             }
;           }
;         }
;       }
	v_pk_fma_f32 v[100:101], v[214:215], v[240:241], v[100:101] op_sel:[1,0,0] op_sel_hi:[0,0,1]
	v_pk_fma_f32 v[96:97], v[222:223], v[248:249], v[96:97] op_sel:[1,0,0] op_sel_hi:[0,0,1]
	v_pk_fma_f32 v[100:101], v[216:217], v[240:241], v[100:101] op_sel:[1,1,0] op_sel_hi:[0,1,1]
	v_pk_fma_f32 v[96:97], v[224:225], v[248:249], v[96:97] op_sel:[1,1,0] op_sel_hi:[0,1,1]
	v_pk_fma_f32 v[100:101], v[218:219], v[242:243], v[100:101] op_sel:[1,0,0] op_sel_hi:[0,0,1]
	v_pk_fma_f32 v[96:97], v[226:227], v[250:251], v[96:97] op_sel:[1,0,0] op_sel_hi:[0,0,1]
	v_pk_fma_f32 v[100:101], v[220:221], v[242:243], v[100:101] op_sel:[1,1,0] op_sel_hi:[0,1,1]
	v_pk_fma_f32 v[96:97], v[228:229], v[250:251], v[96:97] op_sel:[1,1,0] op_sel_hi:[0,1,1]
	ds_read_b128 v[240:243], v172 offset:4096
	ds_read_b128 v[248:251], v172 offset:4352
	s_waitcnt lgkmcnt(2)
	v_pk_fma_f32 v[98:99], v[230:231], v[252:253], v[98:99] op_sel:[1,0,0] op_sel_hi:[0,0,1]
	v_pk_fma_f32 v[94:95], v[182:183], v[176:177], v[94:95] op_sel:[1,0,0] op_sel_hi:[0,0,1]
	v_pk_fma_f32 v[98:99], v[232:233], v[252:253], v[98:99] op_sel:[1,1,0] op_sel_hi:[0,1,1]
	v_pk_fma_f32 v[94:95], v[184:185], v[176:177], v[94:95] op_sel:[1,1,0] op_sel_hi:[0,1,1]
	v_pk_fma_f32 v[98:99], v[234:235], v[254:255], v[98:99] op_sel:[1,0,0] op_sel_hi:[0,0,1]
	v_pk_fma_f32 v[94:95], v[186:187], v[178:179], v[94:95] op_sel:[1,0,0] op_sel_hi:[0,0,1]
	v_pk_fma_f32 v[98:99], v[180:181], v[254:255], v[98:99] op_sel:[1,1,0] op_sel_hi:[0,1,1]
	v_pk_fma_f32 v[94:95], v[188:189], v[178:179], v[94:95] op_sel:[1,1,0] op_sel_hi:[0,1,1]
	ds_read_b128 v[252:255], v172 offset:4608
	ds_read_b128 v[176:179], v172 offset:4864
	s_waitcnt lgkmcnt(2)
	v_pk_fma_f32 v[90:91], v[214:215], v[240:241], v[90:91] op_sel:[0,0,0] op_sel_hi:[1,0,1]
	v_pk_fma_f32 v[86:87], v[222:223], v[248:249], v[86:87] op_sel:[0,0,0] op_sel_hi:[1,0,1]
	v_pk_fma_f32 v[90:91], v[216:217], v[240:241], v[90:91] op_sel:[0,1,0] op_sel_hi:[1,1,1]
	v_pk_fma_f32 v[86:87], v[224:225], v[248:249], v[86:87] op_sel:[0,1,0] op_sel_hi:[1,1,1]
	v_pk_fma_f32 v[90:91], v[218:219], v[242:243], v[90:91] op_sel:[0,0,0] op_sel_hi:[1,0,1]
	v_pk_fma_f32 v[86:87], v[226:227], v[250:251], v[86:87] op_sel:[0,0,0] op_sel_hi:[1,0,1]
	v_pk_fma_f32 v[90:91], v[220:221], v[242:243], v[90:91] op_sel:[0,1,0] op_sel_hi:[1,1,1]
	v_pk_fma_f32 v[86:87], v[228:229], v[250:251], v[86:87] op_sel:[0,1,0] op_sel_hi:[1,1,1]
	ds_read_b128 v[240:243], v172 offset:5120
	ds_read_b128 v[248:251], v172 offset:5376
	s_waitcnt lgkmcnt(2)
	v_pk_fma_f32 v[92:93], v[230:231], v[252:253], v[92:93] op_sel:[0,0,0] op_sel_hi:[1,0,1]
	v_pk_fma_f32 v[88:89], v[182:183], v[176:177], v[88:89] op_sel:[0,0,0] op_sel_hi:[1,0,1]
	v_pk_fma_f32 v[92:93], v[232:233], v[252:253], v[92:93] op_sel:[0,1,0] op_sel_hi:[1,1,1]
	v_pk_fma_f32 v[88:89], v[184:185], v[176:177], v[88:89] op_sel:[0,1,0] op_sel_hi:[1,1,1]
	v_pk_fma_f32 v[92:93], v[234:235], v[254:255], v[92:93] op_sel:[0,0,0] op_sel_hi:[1,0,1]
	v_pk_fma_f32 v[88:89], v[186:187], v[178:179], v[88:89] op_sel:[0,0,0] op_sel_hi:[1,0,1]
	v_pk_fma_f32 v[92:93], v[180:181], v[254:255], v[92:93] op_sel:[0,1,0] op_sel_hi:[1,1,1]
	v_pk_fma_f32 v[88:89], v[188:189], v[178:179], v[88:89] op_sel:[0,1,0] op_sel_hi:[1,1,1]
	ds_read_b128 v[252:255], v172 offset:5632
	ds_read_b128 v[176:179], v172 offset:5888
	s_waitcnt lgkmcnt(2)
	v_pk_fma_f32 v[82:83], v[214:215], v[240:241], v[82:83] op_sel:[0,0,0] op_sel_hi:[1,0,1]
	v_pk_fma_f32 v[78:79], v[222:223], v[248:249], v[78:79] op_sel:[0,0,0] op_sel_hi:[1,0,1]
	v_pk_fma_f32 v[82:83], v[216:217], v[240:241], v[82:83] op_sel:[0,1,0] op_sel_hi:[1,1,1]
	v_pk_fma_f32 v[78:79], v[224:225], v[248:249], v[78:79] op_sel:[0,1,0] op_sel_hi:[1,1,1]
	v_pk_fma_f32 v[82:83], v[218:219], v[242:243], v[82:83] op_sel:[0,0,0] op_sel_hi:[1,0,1]
	v_pk_fma_f32 v[78:79], v[226:227], v[250:251], v[78:79] op_sel:[0,0,0] op_sel_hi:[1,0,1]
	v_pk_fma_f32 v[82:83], v[220:221], v[242:243], v[82:83] op_sel:[0,1,0] op_sel_hi:[1,1,1]
	v_pk_fma_f32 v[78:79], v[228:229], v[250:251], v[78:79] op_sel:[0,1,0] op_sel_hi:[1,1,1]
	ds_read_b128 v[240:243], v172 offset:6144
	ds_read_b128 v[248:251], v172 offset:6400
	s_waitcnt lgkmcnt(2)
; template <bool RWONLY>
; __device__ __forceinline__ void phase_prep(const Params p, int l, char* smem) {
;     ...
;       for (int l4 = 0; l4 < 16; ++l4) {
;         float wv[4][4][2];
; #pragma unroll
;         for (int ll = 0; ll < 4; ++ll) {
; #pragma unroll
;           for (int ch = 0; ch < 2; ++ch) {
;             int c = tid + ch * 256;
;             int li = l4 * 4 + ll;
;             wv[0][ll][ch] = wup[(size_t)(0 * 64 + li) * 512 + c];
;             wv[1][ll][ch] = wup[(size_t)(1 * 64 + li) * 512 + c];
;             wv[2][ll][ch] = aup[(size_t)(0 * 64 + li) * 512 + c];
;             wv[3][ll][ch] = aup[(size_t)(1 * 64 + li) * 512 + c];
;           }
;         }
; #pragma unroll
;         for (int tk = 0; tk < 8; ++tk) {
; #pragma unroll
;           for (int mat = 0; mat < 4; ++mat) {
;             float4 d = *(const float4*)(ld + tk * 256 + mat * 64 + l4 * 4);
; #pragma unroll
;             for (int ch = 0; ch < 2; ++ch) {
;               acc[tk][mat][ch] += d.x * wv[mat][0][ch] + d.y * wv[mat][1][ch] + d.z * wv[mat][2][ch] + d.w * wv[mat][3][ch];
;             }
;           }
;         }
;       }
; #pragma unroll
;       for (int ch = 0; ch < 2; ++ch) {
;         const int c = tid + ch * 256;
;         float shc[3][3];
; #pragma unroll
;         for (int q = 0; q < 3; ++q)
; #pragma unroll
;           for (int j = 0; j < 3; ++j) shc[q][j] = sh[j * 1792 + q * 512 + c];
;         const float kkc = kkp[c], kac = kap[c], rkc = rkp[c];
;         const float w0c0 = w0[c], w0c1 = w0[512 + c], a0c0 = a0[c], a0c1 = a0[512 + c];
;         float um[3], u0[3];
; #pragma unroll
;         for (int q = 0; q < 3; ++q) {
;           um[q] = s0 > 0 ? RWU[(size_t)(s0 - 1) * 1792 + q * 512 + c] : 0.f;
;           u0[q] = RWU[(size_t)s0 * 1792 + q * 512 + c];
	v_pk_fma_f32 v[84:85], v[230:231], v[252:253], v[84:85] op_sel:[0,0,0] op_sel_hi:[1,0,1]
	v_pk_fma_f32 v[80:81], v[182:183], v[176:177], v[80:81] op_sel:[0,0,0] op_sel_hi:[1,0,1]
	v_pk_fma_f32 v[84:85], v[232:233], v[252:253], v[84:85] op_sel:[0,1,0] op_sel_hi:[1,1,1]
	v_pk_fma_f32 v[80:81], v[184:185], v[176:177], v[80:81] op_sel:[0,1,0] op_sel_hi:[1,1,1]
	v_pk_fma_f32 v[84:85], v[234:235], v[254:255], v[84:85] op_sel:[0,0,0] op_sel_hi:[1,0,1]
	v_pk_fma_f32 v[80:81], v[186:187], v[178:179], v[80:81] op_sel:[0,0,0] op_sel_hi:[1,0,1]
	v_pk_fma_f32 v[84:85], v[180:181], v[254:255], v[84:85] op_sel:[0,1,0] op_sel_hi:[1,1,1]
	v_pk_fma_f32 v[80:81], v[188:189], v[178:179], v[80:81] op_sel:[0,1,0] op_sel_hi:[1,1,1]
	ds_read_b128 v[252:255], v172 offset:6656
	ds_read_b128 v[176:179], v172 offset:6912
	s_waitcnt lgkmcnt(2)
	v_pk_fma_f32 v[74:75], v[214:215], v[240:241], v[74:75] op_sel:[0,0,0] op_sel_hi:[1,0,1]
	v_pk_fma_f32 v[70:71], v[222:223], v[248:249], v[70:71] op_sel:[0,0,0] op_sel_hi:[1,0,1]
	v_pk_fma_f32 v[74:75], v[216:217], v[240:241], v[74:75] op_sel:[0,1,0] op_sel_hi:[1,1,1]
	v_pk_fma_f32 v[70:71], v[224:225], v[248:249], v[70:71] op_sel:[0,1,0] op_sel_hi:[1,1,1]
	v_pk_fma_f32 v[74:75], v[218:219], v[242:243], v[74:75] op_sel:[0,0,0] op_sel_hi:[1,0,1]
	v_pk_fma_f32 v[70:71], v[226:227], v[250:251], v[70:71] op_sel:[0,0,0] op_sel_hi:[1,0,1]
	v_pk_fma_f32 v[74:75], v[220:221], v[242:243], v[74:75] op_sel:[0,1,0] op_sel_hi:[1,1,1]
	v_pk_fma_f32 v[70:71], v[228:229], v[250:251], v[70:71] op_sel:[0,1,0] op_sel_hi:[1,1,1]
	ds_read_b128 v[240:243], v172 offset:7168
	ds_read_b128 v[248:251], v172 offset:7424
	s_waitcnt lgkmcnt(2)
	v_pk_fma_f32 v[76:77], v[230:231], v[252:253], v[76:77] op_sel:[0,0,0] op_sel_hi:[1,0,1]
	v_pk_fma_f32 v[72:73], v[182:183], v[176:177], v[72:73] op_sel:[0,0,0] op_sel_hi:[1,0,1]
	v_pk_fma_f32 v[76:77], v[232:233], v[252:253], v[76:77] op_sel:[0,1,0] op_sel_hi:[1,1,1]
	v_pk_fma_f32 v[72:73], v[184:185], v[176:177], v[72:73] op_sel:[0,1,0] op_sel_hi:[1,1,1]
	v_pk_fma_f32 v[76:77], v[234:235], v[254:255], v[76:77] op_sel:[0,0,0] op_sel_hi:[1,0,1]
	v_pk_fma_f32 v[72:73], v[186:187], v[178:179], v[72:73] op_sel:[0,0,0] op_sel_hi:[1,0,1]
	v_pk_fma_f32 v[76:77], v[180:181], v[254:255], v[76:77] op_sel:[0,1,0] op_sel_hi:[1,1,1]
	v_pk_fma_f32 v[72:73], v[188:189], v[178:179], v[72:73] op_sel:[0,1,0] op_sel_hi:[1,1,1]
	ds_read_b128 v[252:255], v172 offset:7680
	ds_read_b128 v[176:179], v172 offset:7936
	s_waitcnt lgkmcnt(2)
	v_pk_fma_f32 v[66:67], v[214:215], v[240:241], v[66:67] op_sel:[0,0,0] op_sel_hi:[1,0,1]
	v_pk_fma_f32 v[62:63], v[222:223], v[248:249], v[62:63] op_sel:[0,0,0] op_sel_hi:[1,0,1]
	v_pk_fma_f32 v[66:67], v[216:217], v[240:241], v[66:67] op_sel:[0,1,0] op_sel_hi:[1,1,1]
	v_pk_fma_f32 v[62:63], v[224:225], v[248:249], v[62:63] op_sel:[0,1,0] op_sel_hi:[1,1,1]
	v_pk_fma_f32 v[66:67], v[218:219], v[242:243], v[66:67] op_sel:[0,0,0] op_sel_hi:[1,0,1]
	v_pk_fma_f32 v[62:63], v[226:227], v[250:251], v[62:63] op_sel:[0,0,0] op_sel_hi:[1,0,1]
	v_pk_fma_f32 v[66:67], v[220:221], v[242:243], v[66:67] op_sel:[0,1,0] op_sel_hi:[1,1,1]
	v_pk_fma_f32 v[62:63], v[228:229], v[250:251], v[62:63] op_sel:[0,1,0] op_sel_hi:[1,1,1]
	s_waitcnt lgkmcnt(0)
	v_pk_fma_f32 v[68:69], v[230:231], v[252:253], v[68:69] op_sel:[0,0,0] op_sel_hi:[1,0,1]
	v_pk_fma_f32 v[64:65], v[182:183], v[176:177], v[64:65] op_sel:[0,0,0] op_sel_hi:[1,0,1]
	v_pk_fma_f32 v[68:69], v[232:233], v[252:253], v[68:69] op_sel:[0,1,0] op_sel_hi:[1,1,1]
	v_pk_fma_f32 v[64:65], v[184:185], v[176:177], v[64:65] op_sel:[0,1,0] op_sel_hi:[1,1,1]
	v_pk_fma_f32 v[68:69], v[234:235], v[254:255], v[68:69] op_sel:[0,0,0] op_sel_hi:[1,0,1]
	v_pk_fma_f32 v[64:65], v[186:187], v[178:179], v[64:65] op_sel:[0,0,0] op_sel_hi:[1,0,1]
	v_pk_fma_f32 v[68:69], v[180:181], v[254:255], v[68:69] op_sel:[0,1,0] op_sel_hi:[1,1,1]
	v_pk_fma_f32 v[64:65], v[188:189], v[178:179], v[64:65] op_sel:[0,1,0] op_sel_hi:[1,1,1]
	s_cmp_eq_u32 s90, 0x20000
	s_cbranch_scc0 .LBB0_365
	global_load_dword v157, v[2:3], off
	global_load_dword v174, v[14:15], off
	global_load_dword v155, v[16:17], off
	global_load_dword v178, v[18:19], off
	global_load_dword v177, v[20:21], off
	global_load_dword v158, v[22:23], off
	global_load_dword v175, v[24:25], off
	global_load_dword v179, v[2:3], off offset:2048
	global_load_dword v156, v[26:27], off
	global_load_dword v176, v[28:29], off
	global_load_dword v153, v[30:31], off
	global_load_dword v152, v[32:33], off
	global_load_dword v173, v[34:35], off
	global_load_dword v154, v[34:35], off offset:2048
	global_load_dword v172, v[36:37], off
	global_load_dword v159, v[36:37], off offset:2048
	s_add_i32 s30, s56, -1
	v_mad_u64_u32 v[130:131], s[30:31], s30, v213, v[38:39]
	v_mov_b32_e32 v132, 0
	s_and_b64 vcc, exec, s[72:73]
	v_mov_b32_e32 v138, 0
	s_cbranch_vccz .LBB0_368
	global_load_dword v138, v[130:131], off
